# v9 + conv LayerNorm wave sums via DPP instead of serialized ds_bpermute
# speedup vs baseline: 1.0079x; 1.0079x over previous
; __device__ __forceinline__ void conv_phase(LAS unsigned char* lds, const bf16* proj, bf16* mix, const float* cw, const float* cb, const float* lng, const float* lnb, const bf16* pwT, int G, int bid) {
;     ...
;         float in[62];
; #pragma unroll
;         for (int i = 0; i < 62; ++i) in[i] = hb[(32 * half + i) * 256 + c];
;         __syncthreads();
; #pragma unroll
;         for (int t = 0; t < 32; ++t) { float acc = bias;
; #pragma unroll
;             for (int j = 0; j < 31; ++j) acc += w[j] * in[t + j];
;             hb[(32 * half + t) * 256 + c] = acc; }
.LBB0_217:
	s_or_b64 exec, exec, s[18:19]
	s_waitcnt lgkmcnt(0)
	s_barrier
	ds_read2st64_b32 v[198:199], v168 offset1:4
	ds_read2st64_b32 v[200:201], v168 offset0:8 offset1:12
	ds_read2st64_b32 v[134:135], v168 offset0:16 offset1:20
	ds_read2st64_b32 v[132:133], v168 offset0:24 offset1:28
	ds_read2st64_b32 v[130:131], v168 offset0:32 offset1:36
	ds_read2st64_b32 v[128:129], v168 offset0:40 offset1:44
	ds_read2st64_b32 v[126:127], v168 offset0:48 offset1:52
	ds_read2st64_b32 v[124:125], v168 offset0:56 offset1:60
	ds_read2st64_b32 v[122:123], v168 offset0:64 offset1:68
	ds_read2st64_b32 v[120:121], v168 offset0:72 offset1:76
	ds_read2st64_b32 v[118:119], v168 offset0:80 offset1:84
	ds_read2st64_b32 v[116:117], v168 offset0:88 offset1:92
	ds_read2st64_b32 v[114:115], v168 offset0:96 offset1:100
	ds_read2st64_b32 v[112:113], v168 offset0:104 offset1:108
	ds_read2st64_b32 v[110:111], v168 offset0:112 offset1:116
	ds_read2st64_b32 v[30:31], v168 offset0:120 offset1:124
	ds_read2st64_b32 v[28:29], v168 offset0:128 offset1:132
	ds_read2st64_b32 v[26:27], v168 offset0:136 offset1:140
	ds_read2st64_b32 v[24:25], v168 offset0:144 offset1:148
	s_waitcnt vmcnt(0)
	ds_read2st64_b32 v[22:23], v168 offset0:152 offset1:156
	ds_read2st64_b32 v[20:21], v168 offset0:160 offset1:164
	ds_read2st64_b32 v[18:19], v168 offset0:168 offset1:172
	ds_read2st64_b32 v[16:17], v168 offset0:176 offset1:180
	ds_read2st64_b32 v[14:15], v168 offset0:184 offset1:188
	ds_read2st64_b32 v[12:13], v168 offset0:192 offset1:196
	ds_read2st64_b32 v[10:11], v168 offset0:200 offset1:204
	ds_read2st64_b32 v[8:9], v168 offset0:208 offset1:212
	ds_read2st64_b32 v[6:7], v168 offset0:216 offset1:220
	ds_read2st64_b32 v[4:5], v168 offset0:224 offset1:228
	ds_read2st64_b32 v[2:3], v168 offset0:232 offset1:236
	ds_read2st64_b32 v[0:1], v168 offset0:240 offset1:244
	s_waitcnt lgkmcnt(14)
	v_fma_f32 v197, v136, v198, v167
	v_fma_f32 v198, v136, v199, v167
	v_fmac_f32_e32 v197, v137, v199
	v_fmac_f32_e32 v198, v137, v200
	v_fmac_f32_e32 v197, v138, v200
	v_fmac_f32_e32 v198, v138, v201
	v_fmac_f32_e32 v197, v139, v201
	v_fmac_f32_e32 v198, v139, v134
	v_fmac_f32_e32 v197, v140, v134
	v_fmac_f32_e32 v198, v140, v135
	v_fmac_f32_e32 v197, v141, v135
	v_fmac_f32_e32 v198, v141, v132
	v_fmac_f32_e32 v197, v142, v132
	v_fmac_f32_e32 v198, v142, v133
	v_fmac_f32_e32 v197, v143, v133
	v_fmac_f32_e32 v198, v143, v130
	v_fmac_f32_e32 v197, v144, v130
	v_fmac_f32_e32 v198, v144, v131
	v_fmac_f32_e32 v197, v145, v131
	v_fmac_f32_e32 v198, v145, v128
	v_fmac_f32_e32 v197, v146, v128
	v_fmac_f32_e32 v198, v146, v129
	v_fmac_f32_e32 v197, v147, v129
	v_fmac_f32_e32 v198, v147, v126
	v_fmac_f32_e32 v197, v148, v126
	v_fmac_f32_e32 v198, v148, v127
	v_fmac_f32_e32 v197, v149, v127
	v_fmac_f32_e32 v198, v149, v124
	v_fmac_f32_e32 v197, v150, v124
	v_fmac_f32_e32 v198, v150, v125
	v_fmac_f32_e32 v197, v151, v125
	v_fmac_f32_e32 v198, v151, v122
	v_fmac_f32_e32 v197, v152, v122
	v_fmac_f32_e32 v198, v152, v123
	v_fmac_f32_e32 v197, v153, v123
	v_fmac_f32_e32 v198, v153, v120
	v_fmac_f32_e32 v197, v154, v120
	v_fmac_f32_e32 v198, v154, v121
	v_fmac_f32_e32 v197, v155, v121
	v_fmac_f32_e32 v198, v155, v118
	v_fmac_f32_e32 v197, v156, v118
	v_fmac_f32_e32 v198, v156, v119
	v_fmac_f32_e32 v197, v157, v119
	v_fmac_f32_e32 v198, v157, v116
	v_fmac_f32_e32 v197, v158, v116
	v_fmac_f32_e32 v198, v158, v117
	v_fmac_f32_e32 v197, v159, v117
	v_fmac_f32_e32 v198, v159, v114
	v_fmac_f32_e32 v197, v160, v114
	v_fmac_f32_e32 v198, v160, v115
	v_fmac_f32_e32 v197, v161, v115
	v_fmac_f32_e32 v198, v161, v112
	v_fmac_f32_e32 v197, v162, v112
	v_fmac_f32_e32 v198, v162, v113
	v_fmac_f32_e32 v197, v163, v113
	v_fmac_f32_e32 v198, v163, v110
	v_fmac_f32_e32 v197, v164, v110
	v_fmac_f32_e32 v198, v164, v111
	v_fmac_f32_e32 v197, v165, v111
	v_fmac_f32_e32 v198, v165, v30
	v_fmac_f32_e32 v197, v166, v30
	v_fmac_f32_e32 v198, v166, v31
	s_waitcnt lgkmcnt(0)
	s_barrier
	ds_write2st64_b32 v168, v197, v198 offset1:4
	v_fma_f32 v197, v136, v200, v167
	v_fmac_f32_e32 v197, v137, v201
	v_fma_f32 v198, v136, v201, v167
	v_fmac_f32_e32 v197, v138, v134
	v_fmac_f32_e32 v198, v137, v134
	v_fma_f32 v134, v136, v134, v167
	v_fmac_f32_e32 v197, v139, v135
	v_fmac_f32_e32 v198, v138, v135
	v_fmac_f32_e32 v134, v137, v135
	v_fma_f32 v135, v136, v135, v167
	v_fmac_f32_e32 v197, v140, v132
	v_fmac_f32_e32 v198, v139, v132
	v_fmac_f32_e32 v134, v138, v132
	v_fmac_f32_e32 v135, v137, v132
	v_fma_f32 v132, v136, v132, v167
	v_fmac_f32_e32 v197, v141, v133
	v_fmac_f32_e32 v198, v140, v133
	v_fmac_f32_e32 v134, v139, v133
	v_fmac_f32_e32 v135, v138, v133
	v_fmac_f32_e32 v132, v137, v133
	v_fma_f32 v133, v136, v133, v167
	v_fmac_f32_e32 v197, v142, v130
	v_fmac_f32_e32 v198, v141, v130
	v_fmac_f32_e32 v134, v140, v130
	v_fmac_f32_e32 v135, v139, v130
	v_fmac_f32_e32 v132, v138, v130
	v_fmac_f32_e32 v133, v137, v130
	v_fma_f32 v130, v136, v130, v167
	v_fmac_f32_e32 v197, v143, v131
	v_fmac_f32_e32 v198, v142, v131
	v_fmac_f32_e32 v134, v141, v131
	v_fmac_f32_e32 v135, v140, v131
	v_fmac_f32_e32 v132, v139, v131
	v_fmac_f32_e32 v133, v138, v131
	v_fmac_f32_e32 v130, v137, v131
	v_fma_f32 v131, v136, v131, v167
	v_fmac_f32_e32 v197, v144, v128
	v_fmac_f32_e32 v198, v143, v128
	v_fmac_f32_e32 v134, v142, v128
	v_fmac_f32_e32 v135, v141, v128
	v_fmac_f32_e32 v132, v140, v128
	v_fmac_f32_e32 v133, v139, v128
	v_fmac_f32_e32 v130, v138, v128
	v_fmac_f32_e32 v131, v137, v128
	v_fma_f32 v128, v136, v128, v167
	v_fmac_f32_e32 v197, v145, v129
	v_fmac_f32_e32 v198, v144, v129
	v_fmac_f32_e32 v134, v143, v129
	v_fmac_f32_e32 v135, v142, v129
	v_fmac_f32_e32 v132, v141, v129
; __device__ __forceinline__ void conv_phase(LAS unsigned char* lds, const bf16* proj, bf16* mix, const float* cw, const float* cb, const float* lng, const float* lnb, const bf16* pwT, int G, int bid) {
;     ...
;         for (int t = 0; t < 32; ++t) { float acc = bias;
; #pragma unroll
;             for (int j = 0; j < 31; ++j) acc += w[j] * in[t + j];
;             hb[(32 * half + t) * 256 + c] = acc; }
	v_fmac_f32_e32 v133, v140, v129
	v_fmac_f32_e32 v130, v139, v129
	v_fmac_f32_e32 v131, v138, v129
	v_fmac_f32_e32 v128, v137, v129
	v_fma_f32 v129, v136, v129, v167
	v_fmac_f32_e32 v197, v146, v126
	v_fmac_f32_e32 v198, v145, v126
	v_fmac_f32_e32 v134, v144, v126
	v_fmac_f32_e32 v135, v143, v126
	v_fmac_f32_e32 v132, v142, v126
	v_fmac_f32_e32 v133, v141, v126
	v_fmac_f32_e32 v130, v140, v126
	v_fmac_f32_e32 v131, v139, v126
	v_fmac_f32_e32 v128, v138, v126
	v_fmac_f32_e32 v129, v137, v126
	v_fma_f32 v126, v136, v126, v167
	v_fmac_f32_e32 v197, v147, v127
	v_fmac_f32_e32 v198, v146, v127
	v_fmac_f32_e32 v134, v145, v127
	v_fmac_f32_e32 v135, v144, v127
	v_fmac_f32_e32 v132, v143, v127
	v_fmac_f32_e32 v133, v142, v127
	v_fmac_f32_e32 v130, v141, v127
	v_fmac_f32_e32 v131, v140, v127
	v_fmac_f32_e32 v128, v139, v127
	v_fmac_f32_e32 v129, v138, v127
	v_fmac_f32_e32 v126, v137, v127
	v_fma_f32 v127, v136, v127, v167
	v_fmac_f32_e32 v197, v148, v124
	v_fmac_f32_e32 v198, v147, v124
	v_fmac_f32_e32 v134, v146, v124
	v_fmac_f32_e32 v135, v145, v124
	v_fmac_f32_e32 v132, v144, v124
	v_fmac_f32_e32 v133, v143, v124
	v_fmac_f32_e32 v130, v142, v124
	v_fmac_f32_e32 v131, v141, v124
	v_fmac_f32_e32 v128, v140, v124
	v_fmac_f32_e32 v129, v139, v124
	v_fmac_f32_e32 v126, v138, v124
	v_fmac_f32_e32 v127, v137, v124
	v_fma_f32 v124, v136, v124, v167
	v_fmac_f32_e32 v197, v149, v125
	v_fmac_f32_e32 v198, v148, v125
	v_fmac_f32_e32 v134, v147, v125
	v_fmac_f32_e32 v135, v146, v125
	v_fmac_f32_e32 v132, v145, v125
	v_fmac_f32_e32 v133, v144, v125
	v_fmac_f32_e32 v130, v143, v125
	v_fmac_f32_e32 v131, v142, v125
	v_fmac_f32_e32 v128, v141, v125
	v_fmac_f32_e32 v129, v140, v125
	v_fmac_f32_e32 v126, v139, v125
	v_fmac_f32_e32 v127, v138, v125
	v_fmac_f32_e32 v124, v137, v125
	v_fma_f32 v125, v136, v125, v167
	v_fmac_f32_e32 v197, v150, v122
	v_fmac_f32_e32 v198, v149, v122
	v_fmac_f32_e32 v134, v148, v122
	v_fmac_f32_e32 v135, v147, v122
	v_fmac_f32_e32 v132, v146, v122
	v_fmac_f32_e32 v133, v145, v122
	v_fmac_f32_e32 v130, v144, v122
	v_fmac_f32_e32 v131, v143, v122
	v_fmac_f32_e32 v128, v142, v122
	v_fmac_f32_e32 v129, v141, v122
	v_fmac_f32_e32 v126, v140, v122
	v_fmac_f32_e32 v127, v139, v122
	v_fmac_f32_e32 v124, v138, v122
	v_fmac_f32_e32 v125, v137, v122
	v_fma_f32 v122, v136, v122, v167
	v_fmac_f32_e32 v197, v151, v123
	v_fmac_f32_e32 v198, v150, v123
	v_fmac_f32_e32 v134, v149, v123
	v_fmac_f32_e32 v135, v148, v123
	v_fmac_f32_e32 v132, v147, v123
	v_fmac_f32_e32 v133, v146, v123
	v_fmac_f32_e32 v130, v145, v123
	v_fmac_f32_e32 v131, v144, v123
	v_fmac_f32_e32 v128, v143, v123
	v_fmac_f32_e32 v129, v142, v123
	v_fmac_f32_e32 v126, v141, v123
	v_fmac_f32_e32 v127, v140, v123
	v_fmac_f32_e32 v124, v139, v123
	v_fmac_f32_e32 v125, v138, v123
	v_fmac_f32_e32 v122, v137, v123
	v_fma_f32 v123, v136, v123, v167
	v_fmac_f32_e32 v197, v152, v120
	v_fmac_f32_e32 v198, v151, v120
	v_fmac_f32_e32 v134, v150, v120
	v_fmac_f32_e32 v135, v149, v120
	v_fmac_f32_e32 v132, v148, v120
	v_fmac_f32_e32 v133, v147, v120
	v_fmac_f32_e32 v130, v146, v120
	v_fmac_f32_e32 v131, v145, v120
	v_fmac_f32_e32 v128, v144, v120
	v_fmac_f32_e32 v129, v143, v120
	v_fmac_f32_e32 v126, v142, v120
	v_fmac_f32_e32 v127, v141, v120
	v_fmac_f32_e32 v124, v140, v120
	v_fmac_f32_e32 v125, v139, v120
	v_fmac_f32_e32 v122, v138, v120
	v_fmac_f32_e32 v123, v137, v120
	v_fma_f32 v120, v136, v120, v167
	v_fmac_f32_e32 v197, v153, v121
	v_fmac_f32_e32 v198, v152, v121
	v_fmac_f32_e32 v134, v151, v121
	v_fmac_f32_e32 v135, v150, v121
	v_fmac_f32_e32 v132, v149, v121
	v_fmac_f32_e32 v133, v148, v121
	v_fmac_f32_e32 v130, v147, v121
	v_fmac_f32_e32 v131, v146, v121
	v_fmac_f32_e32 v128, v145, v121
	v_fmac_f32_e32 v129, v144, v121
	v_fmac_f32_e32 v126, v143, v121
	v_fmac_f32_e32 v127, v142, v121
	v_fmac_f32_e32 v124, v141, v121
	v_fmac_f32_e32 v125, v140, v121
	v_fmac_f32_e32 v122, v139, v121
	v_fmac_f32_e32 v123, v138, v121
	v_fmac_f32_e32 v120, v137, v121
	v_fma_f32 v121, v136, v121, v167
	v_fmac_f32_e32 v197, v154, v118
	v_fmac_f32_e32 v198, v153, v118
	v_fmac_f32_e32 v134, v152, v118
	v_fmac_f32_e32 v135, v151, v118
	v_fmac_f32_e32 v132, v150, v118
	v_fmac_f32_e32 v133, v149, v118
	v_fmac_f32_e32 v130, v148, v118
	v_fmac_f32_e32 v131, v147, v118
	v_fmac_f32_e32 v128, v146, v118
	v_fmac_f32_e32 v129, v145, v118
	v_fmac_f32_e32 v126, v144, v118
	v_fmac_f32_e32 v127, v143, v118
	v_fmac_f32_e32 v124, v142, v118
	v_fmac_f32_e32 v125, v141, v118
	v_fmac_f32_e32 v122, v140, v118
	v_fmac_f32_e32 v123, v139, v118
	v_fmac_f32_e32 v120, v138, v118
	v_fmac_f32_e32 v121, v137, v118
	v_fma_f32 v118, v136, v118, v167
	v_fmac_f32_e32 v197, v155, v119
	v_fmac_f32_e32 v198, v154, v119
	v_fmac_f32_e32 v134, v153, v119
	v_fmac_f32_e32 v135, v152, v119
	v_fmac_f32_e32 v132, v151, v119
	v_fmac_f32_e32 v133, v150, v119
	v_fmac_f32_e32 v130, v149, v119
	v_fmac_f32_e32 v131, v148, v119
	v_fmac_f32_e32 v128, v147, v119
	v_fmac_f32_e32 v129, v146, v119
	v_fmac_f32_e32 v126, v145, v119
	v_fmac_f32_e32 v127, v144, v119
	v_fmac_f32_e32 v124, v143, v119
	v_fmac_f32_e32 v125, v142, v119
	v_fmac_f32_e32 v122, v141, v119
	v_fmac_f32_e32 v123, v140, v119
	v_fmac_f32_e32 v120, v139, v119
	v_fmac_f32_e32 v121, v138, v119
	v_fmac_f32_e32 v118, v137, v119
	v_fma_f32 v119, v136, v119, v167
	v_fmac_f32_e32 v197, v156, v116
	v_fmac_f32_e32 v198, v155, v116
	v_fmac_f32_e32 v134, v154, v116
	v_fmac_f32_e32 v135, v153, v116
	v_fmac_f32_e32 v132, v152, v116
	v_fmac_f32_e32 v133, v151, v116
	v_fmac_f32_e32 v130, v150, v116
	v_fmac_f32_e32 v131, v149, v116
	v_fmac_f32_e32 v128, v148, v116
	v_fmac_f32_e32 v129, v147, v116
	v_fmac_f32_e32 v126, v146, v116
; __device__ __forceinline__ void conv_phase(LAS unsigned char* lds, const bf16* proj, bf16* mix, const float* cw, const float* cb, const float* lng, const float* lnb, const bf16* pwT, int G, int bid) {
;     ...
;         for (int t = 0; t < 32; ++t) { float acc = bias;
; #pragma unroll
;             for (int j = 0; j < 31; ++j) acc += w[j] * in[t + j];
;             hb[(32 * half + t) * 256 + c] = acc; }
	v_fmac_f32_e32 v127, v145, v116
	v_fmac_f32_e32 v124, v144, v116
	v_fmac_f32_e32 v125, v143, v116
	v_fmac_f32_e32 v122, v142, v116
	v_fmac_f32_e32 v123, v141, v116
	v_fmac_f32_e32 v120, v140, v116
	v_fmac_f32_e32 v121, v139, v116
	v_fmac_f32_e32 v118, v138, v116
	v_fmac_f32_e32 v119, v137, v116
	v_fma_f32 v116, v136, v116, v167
	v_fmac_f32_e32 v197, v157, v117
	v_fmac_f32_e32 v198, v156, v117
	v_fmac_f32_e32 v134, v155, v117
	v_fmac_f32_e32 v135, v154, v117
	v_fmac_f32_e32 v132, v153, v117
	v_fmac_f32_e32 v133, v152, v117
	v_fmac_f32_e32 v130, v151, v117
	v_fmac_f32_e32 v131, v150, v117
	v_fmac_f32_e32 v128, v149, v117
	v_fmac_f32_e32 v129, v148, v117
	v_fmac_f32_e32 v126, v147, v117
	v_fmac_f32_e32 v127, v146, v117
	v_fmac_f32_e32 v124, v145, v117
	v_fmac_f32_e32 v125, v144, v117
	v_fmac_f32_e32 v122, v143, v117
	v_fmac_f32_e32 v123, v142, v117
	v_fmac_f32_e32 v120, v141, v117
	v_fmac_f32_e32 v121, v140, v117
	v_fmac_f32_e32 v118, v139, v117
	v_fmac_f32_e32 v119, v138, v117
	v_fmac_f32_e32 v116, v137, v117
	v_fma_f32 v117, v136, v117, v167
	v_fmac_f32_e32 v197, v158, v114
	v_fmac_f32_e32 v198, v157, v114
	v_fmac_f32_e32 v134, v156, v114
	v_fmac_f32_e32 v135, v155, v114
	v_fmac_f32_e32 v132, v154, v114
	v_fmac_f32_e32 v133, v153, v114
	v_fmac_f32_e32 v130, v152, v114
	v_fmac_f32_e32 v131, v151, v114
	v_fmac_f32_e32 v128, v150, v114
	v_fmac_f32_e32 v129, v149, v114
	v_fmac_f32_e32 v126, v148, v114
	v_fmac_f32_e32 v127, v147, v114
	v_fmac_f32_e32 v124, v146, v114
	v_fmac_f32_e32 v125, v145, v114
	v_fmac_f32_e32 v122, v144, v114
	v_fmac_f32_e32 v123, v143, v114
	v_fmac_f32_e32 v120, v142, v114
	v_fmac_f32_e32 v121, v141, v114
	v_fmac_f32_e32 v118, v140, v114
	v_fmac_f32_e32 v119, v139, v114
	v_fmac_f32_e32 v116, v138, v114
	v_fmac_f32_e32 v117, v137, v114
	v_fma_f32 v114, v136, v114, v167
	v_fmac_f32_e32 v197, v159, v115
	v_fmac_f32_e32 v198, v158, v115
	v_fmac_f32_e32 v134, v157, v115
	v_fmac_f32_e32 v135, v156, v115
	v_fmac_f32_e32 v132, v155, v115
	v_fmac_f32_e32 v133, v154, v115
	v_fmac_f32_e32 v130, v153, v115
	v_fmac_f32_e32 v131, v152, v115
	v_fmac_f32_e32 v128, v151, v115
	v_fmac_f32_e32 v129, v150, v115
	v_fmac_f32_e32 v126, v149, v115
	v_fmac_f32_e32 v127, v148, v115
	v_fmac_f32_e32 v124, v147, v115
	v_fmac_f32_e32 v125, v146, v115
	v_fmac_f32_e32 v122, v145, v115
	v_fmac_f32_e32 v123, v144, v115
	v_fmac_f32_e32 v120, v143, v115
	v_fmac_f32_e32 v121, v142, v115
	v_fmac_f32_e32 v118, v141, v115
	v_fmac_f32_e32 v119, v140, v115
	v_fmac_f32_e32 v116, v139, v115
	v_fmac_f32_e32 v117, v138, v115
	v_fmac_f32_e32 v114, v137, v115
	v_fma_f32 v115, v136, v115, v167
	v_fmac_f32_e32 v197, v160, v112
	v_fmac_f32_e32 v198, v159, v112
	v_fmac_f32_e32 v134, v158, v112
	v_fmac_f32_e32 v135, v157, v112
	v_fmac_f32_e32 v132, v156, v112
	v_fmac_f32_e32 v133, v155, v112
	v_fmac_f32_e32 v130, v154, v112
	v_fmac_f32_e32 v131, v153, v112
	v_fmac_f32_e32 v128, v152, v112
	v_fmac_f32_e32 v129, v151, v112
	v_fmac_f32_e32 v126, v150, v112
	v_fmac_f32_e32 v127, v149, v112
	v_fmac_f32_e32 v124, v148, v112
	v_fmac_f32_e32 v125, v147, v112
	v_fmac_f32_e32 v122, v146, v112
	v_fmac_f32_e32 v123, v145, v112
	v_fmac_f32_e32 v120, v144, v112
	v_fmac_f32_e32 v121, v143, v112
	v_fmac_f32_e32 v118, v142, v112
	v_fmac_f32_e32 v119, v141, v112
	v_fmac_f32_e32 v116, v140, v112
	v_fmac_f32_e32 v117, v139, v112
	v_fmac_f32_e32 v114, v138, v112
	v_fmac_f32_e32 v115, v137, v112
	v_fma_f32 v112, v136, v112, v167
	v_fmac_f32_e32 v197, v161, v113
	v_fmac_f32_e32 v198, v160, v113
	v_fmac_f32_e32 v134, v159, v113
	v_fmac_f32_e32 v135, v158, v113
	v_fmac_f32_e32 v132, v157, v113
	v_fmac_f32_e32 v133, v156, v113
	v_fmac_f32_e32 v130, v155, v113
	v_fmac_f32_e32 v131, v154, v113
	v_fmac_f32_e32 v128, v153, v113
	v_fmac_f32_e32 v129, v152, v113
	v_fmac_f32_e32 v126, v151, v113
	v_fmac_f32_e32 v127, v150, v113
	v_fmac_f32_e32 v124, v149, v113
	v_fmac_f32_e32 v125, v148, v113
	v_fmac_f32_e32 v122, v147, v113
	v_fmac_f32_e32 v123, v146, v113
	v_fmac_f32_e32 v120, v145, v113
	v_fmac_f32_e32 v121, v144, v113
	v_fmac_f32_e32 v118, v143, v113
	v_fmac_f32_e32 v119, v142, v113
	v_fmac_f32_e32 v116, v141, v113
	v_fmac_f32_e32 v117, v140, v113
	v_fmac_f32_e32 v114, v139, v113
	v_fmac_f32_e32 v115, v138, v113
	v_fmac_f32_e32 v112, v137, v113
	v_fma_f32 v113, v136, v113, v167
	v_fmac_f32_e32 v197, v162, v110
	v_fmac_f32_e32 v198, v161, v110
	v_fmac_f32_e32 v134, v160, v110
	v_fmac_f32_e32 v135, v159, v110
	v_fmac_f32_e32 v132, v158, v110
	v_fmac_f32_e32 v133, v157, v110
	v_fmac_f32_e32 v130, v156, v110
	v_fmac_f32_e32 v131, v155, v110
	v_fmac_f32_e32 v128, v154, v110
	v_fmac_f32_e32 v129, v153, v110
	v_fmac_f32_e32 v126, v152, v110
	v_fmac_f32_e32 v127, v151, v110
	v_fmac_f32_e32 v124, v150, v110
	v_fmac_f32_e32 v125, v149, v110
	v_fmac_f32_e32 v122, v148, v110
	v_fmac_f32_e32 v123, v147, v110
	v_fmac_f32_e32 v120, v146, v110
	v_fmac_f32_e32 v121, v145, v110
	v_fmac_f32_e32 v118, v144, v110
	v_fmac_f32_e32 v119, v143, v110
	v_fmac_f32_e32 v116, v142, v110
	v_fmac_f32_e32 v117, v141, v110
	v_fmac_f32_e32 v114, v140, v110
	v_fmac_f32_e32 v115, v139, v110
	v_fmac_f32_e32 v112, v138, v110
	v_fmac_f32_e32 v113, v137, v110
	v_fma_f32 v110, v136, v110, v167
	v_fmac_f32_e32 v197, v163, v111
	v_fmac_f32_e32 v198, v162, v111
	v_fmac_f32_e32 v134, v161, v111
	v_fmac_f32_e32 v135, v160, v111
	v_fmac_f32_e32 v132, v159, v111
	v_fmac_f32_e32 v133, v158, v111
	v_fmac_f32_e32 v130, v157, v111
	v_fmac_f32_e32 v131, v156, v111
	v_fmac_f32_e32 v128, v155, v111
	v_fmac_f32_e32 v129, v154, v111
	v_fmac_f32_e32 v126, v153, v111
	v_fmac_f32_e32 v127, v152, v111
	v_fmac_f32_e32 v124, v151, v111
	v_fmac_f32_e32 v125, v150, v111
; __device__ __forceinline__ void conv_phase(LAS unsigned char* lds, const bf16* proj, bf16* mix, const float* cw, const float* cb, const float* lng, const float* lnb, const bf16* pwT, int G, int bid) {
;     ...
;         for (int t = 0; t < 32; ++t) { float acc = bias;
; #pragma unroll
;             for (int j = 0; j < 31; ++j) acc += w[j] * in[t + j];
;             hb[(32 * half + t) * 256 + c] = acc; }
	v_fmac_f32_e32 v122, v149, v111
	v_fmac_f32_e32 v123, v148, v111
	v_fmac_f32_e32 v120, v147, v111
	v_fmac_f32_e32 v121, v146, v111
	v_fmac_f32_e32 v118, v145, v111
	v_fmac_f32_e32 v119, v144, v111
	v_fmac_f32_e32 v116, v143, v111
	v_fmac_f32_e32 v117, v142, v111
	v_fmac_f32_e32 v114, v141, v111
	v_fmac_f32_e32 v115, v140, v111
	v_fmac_f32_e32 v112, v139, v111
	v_fmac_f32_e32 v113, v138, v111
	v_fmac_f32_e32 v110, v137, v111
	v_fma_f32 v111, v136, v111, v167
	v_fmac_f32_e32 v197, v164, v30
	v_fmac_f32_e32 v198, v163, v30
	v_fmac_f32_e32 v134, v162, v30
	v_fmac_f32_e32 v135, v161, v30
	v_fmac_f32_e32 v132, v160, v30
	v_fmac_f32_e32 v133, v159, v30
	v_fmac_f32_e32 v130, v158, v30
	v_fmac_f32_e32 v131, v157, v30
	v_fmac_f32_e32 v128, v156, v30
	v_fmac_f32_e32 v129, v155, v30
	v_fmac_f32_e32 v126, v154, v30
	v_fmac_f32_e32 v127, v153, v30
	v_fmac_f32_e32 v124, v152, v30
	v_fmac_f32_e32 v125, v151, v30
	v_fmac_f32_e32 v122, v150, v30
	v_fmac_f32_e32 v123, v149, v30
	v_fmac_f32_e32 v120, v148, v30
	v_fmac_f32_e32 v121, v147, v30
	v_fmac_f32_e32 v118, v146, v30
	v_fmac_f32_e32 v119, v145, v30
	v_fmac_f32_e32 v116, v144, v30
	v_fmac_f32_e32 v117, v143, v30
	v_fmac_f32_e32 v114, v142, v30
	v_fmac_f32_e32 v115, v141, v30
	v_fmac_f32_e32 v112, v140, v30
	v_fmac_f32_e32 v113, v139, v30
	v_fmac_f32_e32 v110, v138, v30
	v_fmac_f32_e32 v111, v137, v30
	v_fma_f32 v30, v136, v30, v167
	v_fmac_f32_e32 v197, v165, v31
	v_fmac_f32_e32 v198, v164, v31
	v_fmac_f32_e32 v134, v163, v31
	v_fmac_f32_e32 v135, v162, v31
	v_fmac_f32_e32 v132, v161, v31
	v_fmac_f32_e32 v133, v160, v31
	v_fmac_f32_e32 v130, v159, v31
	v_fmac_f32_e32 v131, v158, v31
	v_fmac_f32_e32 v128, v157, v31
	v_fmac_f32_e32 v129, v156, v31
	v_fmac_f32_e32 v126, v155, v31
	v_fmac_f32_e32 v127, v154, v31
	v_fmac_f32_e32 v124, v153, v31
	v_fmac_f32_e32 v125, v152, v31
	v_fmac_f32_e32 v122, v151, v31
	v_fmac_f32_e32 v123, v150, v31
	v_fmac_f32_e32 v120, v149, v31
	v_fmac_f32_e32 v121, v148, v31
	v_fmac_f32_e32 v118, v147, v31
	v_fmac_f32_e32 v119, v146, v31
	v_fmac_f32_e32 v116, v145, v31
	v_fmac_f32_e32 v117, v144, v31
	v_fmac_f32_e32 v114, v143, v31
	v_fmac_f32_e32 v115, v142, v31
	v_fmac_f32_e32 v112, v141, v31
	v_fmac_f32_e32 v113, v140, v31
	v_fmac_f32_e32 v110, v139, v31
	v_fmac_f32_e32 v111, v138, v31
	v_fmac_f32_e32 v30, v137, v31
	v_fma_f32 v31, v136, v31, v167
	v_fmac_f32_e32 v31, v137, v28
	v_fmac_f32_e32 v30, v138, v28
	v_fmac_f32_e32 v31, v138, v29
	v_fmac_f32_e32 v111, v139, v28
	v_fmac_f32_e32 v30, v139, v29
	v_fmac_f32_e32 v31, v139, v26
	v_fmac_f32_e32 v110, v140, v28
	v_fmac_f32_e32 v111, v140, v29
	v_fmac_f32_e32 v30, v140, v26
	v_fmac_f32_e32 v31, v140, v27
	v_fmac_f32_e32 v113, v141, v28
	v_fmac_f32_e32 v110, v141, v29
	v_fmac_f32_e32 v111, v141, v26
	v_fmac_f32_e32 v30, v141, v27
	v_fmac_f32_e32 v31, v141, v24
	v_fmac_f32_e32 v112, v142, v28
	v_fmac_f32_e32 v113, v142, v29
	v_fmac_f32_e32 v110, v142, v26
	v_fmac_f32_e32 v111, v142, v27
	v_fmac_f32_e32 v30, v142, v24
	v_fmac_f32_e32 v31, v142, v25
	v_fmac_f32_e32 v115, v143, v28
	v_fmac_f32_e32 v112, v143, v29
	v_fmac_f32_e32 v113, v143, v26
	v_fmac_f32_e32 v110, v143, v27
	v_fmac_f32_e32 v111, v143, v24
	v_fmac_f32_e32 v30, v143, v25
	v_fmac_f32_e32 v31, v143, v22
	v_fmac_f32_e32 v114, v144, v28
	v_fmac_f32_e32 v115, v144, v29
	v_fmac_f32_e32 v112, v144, v26
	v_fmac_f32_e32 v113, v144, v27
	v_fmac_f32_e32 v110, v144, v24
	v_fmac_f32_e32 v111, v144, v25
	v_fmac_f32_e32 v30, v144, v22
	v_fmac_f32_e32 v31, v144, v23
	v_fmac_f32_e32 v117, v145, v28
	v_fmac_f32_e32 v114, v145, v29
	v_fmac_f32_e32 v115, v145, v26
	v_fmac_f32_e32 v112, v145, v27
	v_fmac_f32_e32 v113, v145, v24
	v_fmac_f32_e32 v110, v145, v25
	v_fmac_f32_e32 v111, v145, v22
	v_fmac_f32_e32 v30, v145, v23
	v_fmac_f32_e32 v31, v145, v20
	v_fmac_f32_e32 v116, v146, v28
	v_fmac_f32_e32 v117, v146, v29
	v_fmac_f32_e32 v114, v146, v26
	v_fmac_f32_e32 v115, v146, v27
	v_fmac_f32_e32 v112, v146, v24
	v_fmac_f32_e32 v113, v146, v25
	v_fmac_f32_e32 v110, v146, v22
	v_fmac_f32_e32 v111, v146, v23
	v_fmac_f32_e32 v30, v146, v20
	v_fmac_f32_e32 v31, v146, v21
	v_fmac_f32_e32 v119, v147, v28
	v_fmac_f32_e32 v116, v147, v29
	v_fmac_f32_e32 v117, v147, v26
	v_fmac_f32_e32 v114, v147, v27
	v_fmac_f32_e32 v115, v147, v24
	v_fmac_f32_e32 v112, v147, v25
	v_fmac_f32_e32 v113, v147, v22
	v_fmac_f32_e32 v110, v147, v23
	v_fmac_f32_e32 v111, v147, v20
	v_fmac_f32_e32 v30, v147, v21
	v_fmac_f32_e32 v31, v147, v18
	v_fmac_f32_e32 v118, v148, v28
	v_fmac_f32_e32 v119, v148, v29
	v_fmac_f32_e32 v116, v148, v26
	v_fmac_f32_e32 v117, v148, v27
	v_fmac_f32_e32 v114, v148, v24
	v_fmac_f32_e32 v115, v148, v25
	v_fmac_f32_e32 v112, v148, v22
	v_fmac_f32_e32 v113, v148, v23
	v_fmac_f32_e32 v110, v148, v20
	v_fmac_f32_e32 v111, v148, v21
	v_fmac_f32_e32 v30, v148, v18
	v_fmac_f32_e32 v31, v148, v19
	v_fmac_f32_e32 v121, v149, v28
	v_fmac_f32_e32 v118, v149, v29
	v_fmac_f32_e32 v119, v149, v26
	v_fmac_f32_e32 v116, v149, v27
	v_fmac_f32_e32 v117, v149, v24
	v_fmac_f32_e32 v114, v149, v25
	v_fmac_f32_e32 v115, v149, v22
	v_fmac_f32_e32 v112, v149, v23
	v_fmac_f32_e32 v113, v149, v20
	v_fmac_f32_e32 v110, v149, v21
	v_fmac_f32_e32 v111, v149, v18
	v_fmac_f32_e32 v30, v149, v19
	v_fmac_f32_e32 v31, v149, v16
	v_fmac_f32_e32 v120, v150, v28
	v_fmac_f32_e32 v121, v150, v29
	v_fmac_f32_e32 v118, v150, v26
	v_fmac_f32_e32 v119, v150, v27
	v_fmac_f32_e32 v116, v150, v24
	v_fmac_f32_e32 v117, v150, v25
	v_fmac_f32_e32 v114, v150, v22
	v_fmac_f32_e32 v115, v150, v23
	v_fmac_f32_e32 v112, v150, v20
	v_fmac_f32_e32 v113, v150, v21
	v_fmac_f32_e32 v110, v150, v18
	v_fmac_f32_e32 v111, v150, v19
	v_fmac_f32_e32 v30, v150, v16
; __device__ __forceinline__ void conv_phase(LAS unsigned char* lds, const bf16* proj, bf16* mix, const float* cw, const float* cb, const float* lng, const float* lnb, const bf16* pwT, int G, int bid) {
;     ...
;         for (int t = 0; t < 32; ++t) { float acc = bias;
; #pragma unroll
;             for (int j = 0; j < 31; ++j) acc += w[j] * in[t + j];
;             hb[(32 * half + t) * 256 + c] = acc; }
	v_fmac_f32_e32 v31, v150, v17
	v_fmac_f32_e32 v123, v151, v28
	v_fmac_f32_e32 v120, v151, v29
	v_fmac_f32_e32 v121, v151, v26
	v_fmac_f32_e32 v118, v151, v27
	v_fmac_f32_e32 v119, v151, v24
	v_fmac_f32_e32 v116, v151, v25
	v_fmac_f32_e32 v117, v151, v22
	v_fmac_f32_e32 v114, v151, v23
	v_fmac_f32_e32 v115, v151, v20
	v_fmac_f32_e32 v112, v151, v21
	v_fmac_f32_e32 v113, v151, v18
	v_fmac_f32_e32 v110, v151, v19
	v_fmac_f32_e32 v111, v151, v16
	v_fmac_f32_e32 v30, v151, v17
	v_fmac_f32_e32 v31, v151, v14
	v_fmac_f32_e32 v122, v152, v28
	v_fmac_f32_e32 v123, v152, v29
	v_fmac_f32_e32 v120, v152, v26
	v_fmac_f32_e32 v121, v152, v27
	v_fmac_f32_e32 v118, v152, v24
	v_fmac_f32_e32 v119, v152, v25
	v_fmac_f32_e32 v116, v152, v22
	v_fmac_f32_e32 v117, v152, v23
	v_fmac_f32_e32 v114, v152, v20
	v_fmac_f32_e32 v115, v152, v21
	v_fmac_f32_e32 v112, v152, v18
	v_fmac_f32_e32 v113, v152, v19
	v_fmac_f32_e32 v110, v152, v16
	v_fmac_f32_e32 v111, v152, v17
	v_fmac_f32_e32 v30, v152, v14
	v_fmac_f32_e32 v31, v152, v15
	v_fmac_f32_e32 v125, v153, v28
	v_fmac_f32_e32 v122, v153, v29
	v_fmac_f32_e32 v123, v153, v26
	v_fmac_f32_e32 v120, v153, v27
	v_fmac_f32_e32 v121, v153, v24
	v_fmac_f32_e32 v118, v153, v25
	v_fmac_f32_e32 v119, v153, v22
	v_fmac_f32_e32 v116, v153, v23
	v_fmac_f32_e32 v117, v153, v20
	v_fmac_f32_e32 v114, v153, v21
	v_fmac_f32_e32 v115, v153, v18
	v_fmac_f32_e32 v112, v153, v19
	v_fmac_f32_e32 v113, v153, v16
	v_fmac_f32_e32 v110, v153, v17
	v_fmac_f32_e32 v111, v153, v14
	v_fmac_f32_e32 v30, v153, v15
	v_fmac_f32_e32 v31, v153, v12
	v_fmac_f32_e32 v124, v154, v28
	v_fmac_f32_e32 v125, v154, v29
	v_fmac_f32_e32 v122, v154, v26
	v_fmac_f32_e32 v123, v154, v27
	v_fmac_f32_e32 v120, v154, v24
	v_fmac_f32_e32 v121, v154, v25
	v_fmac_f32_e32 v118, v154, v22
	v_fmac_f32_e32 v119, v154, v23
	v_fmac_f32_e32 v116, v154, v20
	v_fmac_f32_e32 v117, v154, v21
	v_fmac_f32_e32 v114, v154, v18
	v_fmac_f32_e32 v115, v154, v19
	v_fmac_f32_e32 v112, v154, v16
	v_fmac_f32_e32 v113, v154, v17
	v_fmac_f32_e32 v110, v154, v14
	v_fmac_f32_e32 v111, v154, v15
	v_fmac_f32_e32 v30, v154, v12
	v_fmac_f32_e32 v31, v154, v13
	v_fmac_f32_e32 v127, v155, v28
	v_fmac_f32_e32 v124, v155, v29
	v_fmac_f32_e32 v125, v155, v26
	v_fmac_f32_e32 v122, v155, v27
	v_fmac_f32_e32 v123, v155, v24
	v_fmac_f32_e32 v120, v155, v25
	v_fmac_f32_e32 v121, v155, v22
	v_fmac_f32_e32 v118, v155, v23
	v_fmac_f32_e32 v119, v155, v20
	v_fmac_f32_e32 v116, v155, v21
	v_fmac_f32_e32 v117, v155, v18
	v_fmac_f32_e32 v114, v155, v19
	v_fmac_f32_e32 v115, v155, v16
	v_fmac_f32_e32 v112, v155, v17
	v_fmac_f32_e32 v113, v155, v14
	v_fmac_f32_e32 v110, v155, v15
	v_fmac_f32_e32 v111, v155, v12
	v_fmac_f32_e32 v30, v155, v13
	v_fmac_f32_e32 v31, v155, v10
	v_fmac_f32_e32 v126, v156, v28
	v_fmac_f32_e32 v127, v156, v29
	v_fmac_f32_e32 v124, v156, v26
	v_fmac_f32_e32 v125, v156, v27
	v_fmac_f32_e32 v122, v156, v24
	v_fmac_f32_e32 v123, v156, v25
	v_fmac_f32_e32 v120, v156, v22
	v_fmac_f32_e32 v121, v156, v23
	v_fmac_f32_e32 v118, v156, v20
	v_fmac_f32_e32 v119, v156, v21
	v_fmac_f32_e32 v116, v156, v18
	v_fmac_f32_e32 v117, v156, v19
	v_fmac_f32_e32 v114, v156, v16
	v_fmac_f32_e32 v115, v156, v17
	v_fmac_f32_e32 v112, v156, v14
	v_fmac_f32_e32 v113, v156, v15
	v_fmac_f32_e32 v110, v156, v12
	v_fmac_f32_e32 v111, v156, v13
	v_fmac_f32_e32 v30, v156, v10
	v_fmac_f32_e32 v31, v156, v11
	v_fmac_f32_e32 v129, v157, v28
	v_fmac_f32_e32 v126, v157, v29
	v_fmac_f32_e32 v127, v157, v26
	v_fmac_f32_e32 v124, v157, v27
	v_fmac_f32_e32 v125, v157, v24
	v_fmac_f32_e32 v122, v157, v25
	v_fmac_f32_e32 v123, v157, v22
	v_fmac_f32_e32 v120, v157, v23
	v_fmac_f32_e32 v121, v157, v20
	v_fmac_f32_e32 v118, v157, v21
	v_fmac_f32_e32 v119, v157, v18
	v_fmac_f32_e32 v116, v157, v19
	v_fmac_f32_e32 v117, v157, v16
	v_fmac_f32_e32 v114, v157, v17
	v_fmac_f32_e32 v115, v157, v14
	v_fmac_f32_e32 v112, v157, v15
	v_fmac_f32_e32 v113, v157, v12
	v_fmac_f32_e32 v110, v157, v13
	v_fmac_f32_e32 v111, v157, v10
	v_fmac_f32_e32 v30, v157, v11
	v_fmac_f32_e32 v31, v157, v8
	v_fmac_f32_e32 v128, v158, v28
	v_fmac_f32_e32 v129, v158, v29
	v_fmac_f32_e32 v126, v158, v26
	v_fmac_f32_e32 v127, v158, v27
	v_fmac_f32_e32 v124, v158, v24
	v_fmac_f32_e32 v125, v158, v25
	v_fmac_f32_e32 v122, v158, v22
	v_fmac_f32_e32 v123, v158, v23
	v_fmac_f32_e32 v120, v158, v20
	v_fmac_f32_e32 v121, v158, v21
	v_fmac_f32_e32 v118, v158, v18
	v_fmac_f32_e32 v119, v158, v19
	v_fmac_f32_e32 v116, v158, v16
	v_fmac_f32_e32 v117, v158, v17
	v_fmac_f32_e32 v114, v158, v14
	v_fmac_f32_e32 v115, v158, v15
	v_fmac_f32_e32 v112, v158, v12
	v_fmac_f32_e32 v113, v158, v13
	v_fmac_f32_e32 v110, v158, v10
	v_fmac_f32_e32 v111, v158, v11
	v_fmac_f32_e32 v30, v158, v8
	v_fmac_f32_e32 v31, v158, v9
	v_fmac_f32_e32 v131, v159, v28
	v_fmac_f32_e32 v128, v159, v29
	v_fmac_f32_e32 v129, v159, v26
	v_fmac_f32_e32 v126, v159, v27
	v_fmac_f32_e32 v127, v159, v24
	v_fmac_f32_e32 v124, v159, v25
	v_fmac_f32_e32 v125, v159, v22
	v_fmac_f32_e32 v122, v159, v23
	v_fmac_f32_e32 v123, v159, v20
	v_fmac_f32_e32 v120, v159, v21
	v_fmac_f32_e32 v121, v159, v18
	v_fmac_f32_e32 v118, v159, v19
	v_fmac_f32_e32 v119, v159, v16
	v_fmac_f32_e32 v116, v159, v17
	v_fmac_f32_e32 v117, v159, v14
	v_fmac_f32_e32 v114, v159, v15
	v_fmac_f32_e32 v115, v159, v12
	v_fmac_f32_e32 v112, v159, v13
	v_fmac_f32_e32 v113, v159, v10
	v_fmac_f32_e32 v110, v159, v11
	v_fmac_f32_e32 v111, v159, v8
	v_fmac_f32_e32 v30, v159, v9
	v_fmac_f32_e32 v31, v159, v6
	v_fmac_f32_e32 v130, v160, v28
	v_fmac_f32_e32 v131, v160, v29
	v_fmac_f32_e32 v128, v160, v26
	v_fmac_f32_e32 v129, v160, v27
	v_fmac_f32_e32 v126, v160, v24
; #define LAS __attribute__((address_space(3)))
; __device__ __forceinline__ void conv_phase(LAS unsigned char* lds, const bf16* proj, bf16* mix, const float* cw, const float* cb, const float* lng, const float* lnb, const bf16* pwT, int G, int bid) {
;     ...
;         for (int t = 0; t < 32; ++t) { float acc = bias;
; #pragma unroll
;             for (int j = 0; j < 31; ++j) acc += w[j] * in[t + j];
;             hb[(32 * half + t) * 256 + c] = acc; }
;         __syncthreads();
; #pragma unroll
;         for (int tt = 0; tt < 8; ++tt) { const int tk = 8 * wid + tt; const f32x4 v = *(const LAS f32x4*)(hb + tk * 256 + 4 * lane);
	v_fmac_f32_e32 v127, v160, v25
	v_fmac_f32_e32 v124, v160, v22
	v_fmac_f32_e32 v125, v160, v23
	v_fmac_f32_e32 v122, v160, v20
	v_fmac_f32_e32 v123, v160, v21
	v_fmac_f32_e32 v120, v160, v18
	v_fmac_f32_e32 v121, v160, v19
	v_fmac_f32_e32 v118, v160, v16
	v_fmac_f32_e32 v119, v160, v17
	v_fmac_f32_e32 v116, v160, v14
	v_fmac_f32_e32 v117, v160, v15
	v_fmac_f32_e32 v114, v160, v12
	v_fmac_f32_e32 v115, v160, v13
	v_fmac_f32_e32 v112, v160, v10
	v_fmac_f32_e32 v113, v160, v11
	v_fmac_f32_e32 v110, v160, v8
	v_fmac_f32_e32 v111, v160, v9
	v_fmac_f32_e32 v30, v160, v6
	v_fmac_f32_e32 v31, v160, v7
	v_fmac_f32_e32 v133, v161, v28
	v_fmac_f32_e32 v130, v161, v29
	v_fmac_f32_e32 v131, v161, v26
	v_fmac_f32_e32 v128, v161, v27
	v_fmac_f32_e32 v129, v161, v24
	v_fmac_f32_e32 v126, v161, v25
	v_fmac_f32_e32 v127, v161, v22
	v_fmac_f32_e32 v124, v161, v23
	v_fmac_f32_e32 v125, v161, v20
	v_fmac_f32_e32 v122, v161, v21
	v_fmac_f32_e32 v123, v161, v18
	v_fmac_f32_e32 v120, v161, v19
	v_fmac_f32_e32 v121, v161, v16
	v_fmac_f32_e32 v118, v161, v17
	v_fmac_f32_e32 v119, v161, v14
	v_fmac_f32_e32 v116, v161, v15
	v_fmac_f32_e32 v117, v161, v12
	v_fmac_f32_e32 v114, v161, v13
	v_fmac_f32_e32 v115, v161, v10
	v_fmac_f32_e32 v112, v161, v11
	v_fmac_f32_e32 v113, v161, v8
	v_fmac_f32_e32 v110, v161, v9
	v_fmac_f32_e32 v111, v161, v6
	v_fmac_f32_e32 v30, v161, v7
	v_fmac_f32_e32 v31, v161, v4
	v_fmac_f32_e32 v132, v162, v28
	v_fmac_f32_e32 v133, v162, v29
	v_fmac_f32_e32 v130, v162, v26
	v_fmac_f32_e32 v131, v162, v27
	v_fmac_f32_e32 v128, v162, v24
	v_fmac_f32_e32 v129, v162, v25
	v_fmac_f32_e32 v126, v162, v22
	v_fmac_f32_e32 v127, v162, v23
	v_fmac_f32_e32 v124, v162, v20
	v_fmac_f32_e32 v125, v162, v21
	v_fmac_f32_e32 v122, v162, v18
	v_fmac_f32_e32 v123, v162, v19
	v_fmac_f32_e32 v120, v162, v16
	v_fmac_f32_e32 v121, v162, v17
	v_fmac_f32_e32 v118, v162, v14
	v_fmac_f32_e32 v119, v162, v15
	v_fmac_f32_e32 v116, v162, v12
	v_fmac_f32_e32 v117, v162, v13
	v_fmac_f32_e32 v114, v162, v10
	v_fmac_f32_e32 v115, v162, v11
	v_fmac_f32_e32 v112, v162, v8
	v_fmac_f32_e32 v113, v162, v9
	v_fmac_f32_e32 v110, v162, v6
	v_fmac_f32_e32 v111, v162, v7
	v_fmac_f32_e32 v30, v162, v4
	v_fmac_f32_e32 v31, v162, v5
	v_fmac_f32_e32 v135, v163, v28
	v_fmac_f32_e32 v132, v163, v29
	v_fmac_f32_e32 v133, v163, v26
	v_fmac_f32_e32 v130, v163, v27
	v_fmac_f32_e32 v131, v163, v24
	v_fmac_f32_e32 v128, v163, v25
	v_fmac_f32_e32 v129, v163, v22
	v_fmac_f32_e32 v126, v163, v23
	v_fmac_f32_e32 v127, v163, v20
	v_fmac_f32_e32 v124, v163, v21
	v_fmac_f32_e32 v125, v163, v18
	v_fmac_f32_e32 v122, v163, v19
	v_fmac_f32_e32 v123, v163, v16
	v_fmac_f32_e32 v120, v163, v17
	v_fmac_f32_e32 v121, v163, v14
	v_fmac_f32_e32 v118, v163, v15
	v_fmac_f32_e32 v119, v163, v12
	v_fmac_f32_e32 v116, v163, v13
	v_fmac_f32_e32 v117, v163, v10
	v_fmac_f32_e32 v114, v163, v11
	v_fmac_f32_e32 v115, v163, v8
	v_fmac_f32_e32 v112, v163, v9
	v_fmac_f32_e32 v113, v163, v6
	v_fmac_f32_e32 v110, v163, v7
	v_fmac_f32_e32 v111, v163, v4
	v_fmac_f32_e32 v30, v163, v5
	v_fmac_f32_e32 v31, v163, v2
	v_fmac_f32_e32 v134, v164, v28
	v_fmac_f32_e32 v135, v164, v29
	v_fmac_f32_e32 v132, v164, v26
	v_fmac_f32_e32 v133, v164, v27
	v_fmac_f32_e32 v130, v164, v24
	v_fmac_f32_e32 v131, v164, v25
	v_fmac_f32_e32 v128, v164, v22
	v_fmac_f32_e32 v129, v164, v23
	v_fmac_f32_e32 v126, v164, v20
	v_fmac_f32_e32 v127, v164, v21
	v_fmac_f32_e32 v124, v164, v18
	v_fmac_f32_e32 v125, v164, v19
	v_fmac_f32_e32 v122, v164, v16
	v_fmac_f32_e32 v123, v164, v17
	v_fmac_f32_e32 v120, v164, v14
	v_fmac_f32_e32 v121, v164, v15
	v_fmac_f32_e32 v118, v164, v12
	v_fmac_f32_e32 v119, v164, v13
	v_fmac_f32_e32 v116, v164, v10
	v_fmac_f32_e32 v117, v164, v11
	v_fmac_f32_e32 v114, v164, v8
	v_fmac_f32_e32 v115, v164, v9
	v_fmac_f32_e32 v112, v164, v6
	v_fmac_f32_e32 v113, v164, v7
	v_fmac_f32_e32 v110, v164, v4
	v_fmac_f32_e32 v111, v164, v5
	v_fmac_f32_e32 v30, v164, v2
	v_fmac_f32_e32 v31, v164, v3
	v_fmac_f32_e32 v198, v165, v28
	v_fmac_f32_e32 v134, v165, v29
	v_fmac_f32_e32 v135, v165, v26
	v_fmac_f32_e32 v132, v165, v27
	v_fmac_f32_e32 v133, v165, v24
	v_fmac_f32_e32 v130, v165, v25
	v_fmac_f32_e32 v131, v165, v22
	v_fmac_f32_e32 v128, v165, v23
	v_fmac_f32_e32 v129, v165, v20
	v_fmac_f32_e32 v126, v165, v21
	v_fmac_f32_e32 v127, v165, v18
	v_fmac_f32_e32 v124, v165, v19
	v_fmac_f32_e32 v125, v165, v16
	v_fmac_f32_e32 v122, v165, v17
	v_fmac_f32_e32 v123, v165, v14
	v_fmac_f32_e32 v120, v165, v15
	v_fmac_f32_e32 v121, v165, v12
	v_fmac_f32_e32 v118, v165, v13
	v_fmac_f32_e32 v119, v165, v10
	v_fmac_f32_e32 v116, v165, v11
	v_fmac_f32_e32 v117, v165, v8
	v_fmac_f32_e32 v114, v165, v9
	v_fmac_f32_e32 v115, v165, v6
	v_fmac_f32_e32 v112, v165, v7
	v_fmac_f32_e32 v113, v165, v4
	v_fmac_f32_e32 v110, v165, v5
	v_fmac_f32_e32 v111, v165, v2
	v_fmac_f32_e32 v30, v165, v3
	v_fmac_f32_e32 v31, v165, v0
	v_fmac_f32_e32 v197, v166, v28
	v_fmac_f32_e32 v198, v166, v29
	v_fmac_f32_e32 v134, v166, v26
	v_fmac_f32_e32 v135, v166, v27
	v_fmac_f32_e32 v132, v166, v24
	v_fmac_f32_e32 v133, v166, v25
	v_fmac_f32_e32 v130, v166, v22
	v_fmac_f32_e32 v131, v166, v23
	v_fmac_f32_e32 v128, v166, v20
	v_fmac_f32_e32 v129, v166, v21
	v_fmac_f32_e32 v126, v166, v18
	v_fmac_f32_e32 v127, v166, v19
	v_fmac_f32_e32 v124, v166, v16
	v_fmac_f32_e32 v125, v166, v17
	v_fmac_f32_e32 v122, v166, v14
	v_fmac_f32_e32 v123, v166, v15
	v_fmac_f32_e32 v120, v166, v12
	v_fmac_f32_e32 v121, v166, v13
	v_fmac_f32_e32 v118, v166, v10
	v_fmac_f32_e32 v119, v166, v11
	v_fmac_f32_e32 v116, v166, v8
	v_fmac_f32_e32 v117, v166, v9
	v_fmac_f32_e32 v114, v166, v6
	v_fmac_f32_e32 v115, v166, v7
	v_fmac_f32_e32 v112, v166, v4
	v_fmac_f32_e32 v113, v166, v5
	v_fmac_f32_e32 v110, v166, v2
	v_fmac_f32_e32 v111, v166, v3
	v_fmac_f32_e32 v30, v166, v0
	v_fmac_f32_e32 v31, v166, v1
	v_add_u32_e32 v0, s20, v169
	ds_write2st64_b32 v168, v197, v198 offset0:8 offset1:12
	ds_write2st64_b32 v168, v134, v135 offset0:16 offset1:20
	ds_write2st64_b32 v168, v132, v133 offset0:24 offset1:28
	ds_write2st64_b32 v168, v130, v131 offset0:32 offset1:36
	ds_write2st64_b32 v168, v128, v129 offset0:40 offset1:44
	ds_write2st64_b32 v168, v126, v127 offset0:48 offset1:52
	ds_write2st64_b32 v168, v124, v125 offset0:56 offset1:60
	ds_write2st64_b32 v168, v122, v123 offset0:64 offset1:68
	ds_write2st64_b32 v168, v120, v121 offset0:72 offset1:76
	ds_write2st64_b32 v168, v118, v119 offset0:80 offset1:84
	ds_write2st64_b32 v168, v116, v117 offset0:88 offset1:92
	ds_write2st64_b32 v168, v114, v115 offset0:96 offset1:100
	ds_write2st64_b32 v168, v112, v113 offset0:104 offset1:108
	ds_write2st64_b32 v168, v110, v111 offset0:112 offset1:116
	ds_write2st64_b32 v168, v30, v31 offset0:120 offset1:124
	s_waitcnt lgkmcnt(0)
	s_barrier
; #define LAS __attribute__((address_space(3)))
; __device__ __forceinline__ unsigned pk2(float lo, float hi) { const f32x2_t v = {lo, hi}; const bf16x2_t b = __builtin_convertvector(v, bf16x2_t); return __builtin_bit_cast(unsigned, b); }
; __device__ __forceinline__ float sigmoidf_(float x) { return __builtin_amdgcn_rcpf(1.0f + __builtin_amdgcn_exp2f(-1.4426950408889634f * x)); }
; __device__ __forceinline__ float wave_sum(float v) {
; #pragma unroll
;     for (int o = 1; o < 64; o <<= 1) v += __shfl_xor(v, o);
;     return v;
; __device__ __forceinline__ void conv_phase(LAS unsigned char* lds, const bf16* proj, bf16* mix, const float* cw, const float* cb, const float* lng, const float* lnb, const bf16* pwT, int G, int bid) {
;     ...
;         for (int tt = 0; tt < 8; ++tt) { const int tk = 8 * wid + tt; const f32x4 v = *(const LAS f32x4*)(hb + tk * 256 + 4 * lane);
;             const float mean = wave_sum((v[0] + v[1]) + (v[2] + v[3])) * (1.0f / 256.0f); const f32x4 d = v - mean;
;             const float var = wave_sum((d[0] * d[0] + d[1] * d[1]) + (d[2] * d[2] + d[3] * d[3])) * (1.0f / 256.0f); const float rstd = __builtin_amdgcn_rsqf(var + 1e-5f);
;             f32x4 y = d * rstd * gg + bb;
; #pragma unroll
;             for (int i = 0; i < 4; ++i) y[i] = y[i] * sigmoidf_(y[i]);
;             u32x2 o; o.x = pk2(y[0], y[1]); o.y = pk2(y[2], y[3]); *(LAS u32x2*)(ab + tk * CV_APITCH + lane * 8) = o; }
	ds_read_b128 v[0:3], v0
	s_ashr_i32 s17, s16, 31
	s_lshl_b64 s[0:1], s[16:17], 11
	s_add_i32 s30, s30, s60
	s_add_i32 s16, s16, s62
	s_waitcnt lgkmcnt(0)
	v_mov_b32_e32 v4, v1
	v_mov_b32_e32 v5, v2
	v_mov_b32_e32 v6, v0
	v_mov_b32_e32 v7, v3
	v_pk_add_f32 v[4:5], v[4:5], v[6:7]
	s_cmpk_gt_i32 s30, 0x3ff
	v_add_f32_e32 v4, v4, v5
	s_nop 1
	v_add_f32_dpp v4, v4, v4 quad_perm:[1,0,3,2] row_mask:0xf bank_mask:0xf
	s_nop 1
	v_add_f32_dpp v4, v4, v4 quad_perm:[2,3,0,1] row_mask:0xf bank_mask:0xf
	s_nop 1
	v_add_f32_dpp v4, v4, v4 row_half_mirror row_mask:0xf bank_mask:0xf
	s_nop 1
	v_add_f32_dpp v4, v4, v4 row_mirror row_mask:0xf bank_mask:0xf
	s_nop 1
	v_add_f32_dpp v4, v4, v4 row_bcast:15 row_mask:0xa bank_mask:0xf
	s_nop 1
	v_add_f32_dpp v4, v4, v4 row_bcast:31 row_mask:0xc bank_mask:0xf
	s_nop 1
	v_readlane_b32 s101, v4, 63
	s_nop 1
	v_mov_b32_e32 v4, s101
	v_fmamk_f32 v1, v4, 0xbb800000, v1
	v_fmamk_f32 v0, v4, 0xbb800000, v0
	v_fmamk_f32 v3, v4, 0xbb800000, v3
	v_fmac_f32_e32 v2, 0xbb800000, v4
	v_pk_mul_f32 v[4:5], v[2:3], v[2:3]
	v_pk_mul_f32 v[6:7], v[0:1], v[0:1]
	s_nop 0
	v_pk_mov_b32 v[8:9], v[6:7], v[4:5] op_sel:[1,0]
	v_mov_b32_e32 v7, v5
	v_pk_add_f32 v[4:5], v[8:9], v[6:7]
	s_nop 0
	v_add_f32_e32 v4, v4, v5
	s_nop 1
	v_add_f32_dpp v4, v4, v4 quad_perm:[1,0,3,2] row_mask:0xf bank_mask:0xf
	s_nop 1
	v_add_f32_dpp v4, v4, v4 quad_perm:[2,3,0,1] row_mask:0xf bank_mask:0xf
	s_nop 1
	v_add_f32_dpp v4, v4, v4 row_half_mirror row_mask:0xf bank_mask:0xf
	s_nop 1
	v_add_f32_dpp v4, v4, v4 row_mirror row_mask:0xf bank_mask:0xf
	s_nop 1
	v_add_f32_dpp v4, v4, v4 row_bcast:15 row_mask:0xa bank_mask:0xf
	s_nop 1
	v_add_f32_dpp v4, v4, v4 row_bcast:31 row_mask:0xc bank_mask:0xf
	s_nop 1
	v_readlane_b32 s101, v4, 63
	s_nop 1
	v_mov_b32_e32 v4, s101
	v_fmamk_f32 v4, v4, 0x3b800000, v210
	v_rsq_f32_e32 v4, v4
	s_nop 0
	v_pk_mul_f32 v[0:1], v[0:1], v[4:5] op_sel_hi:[1,0]
	v_pk_mul_f32 v[2:3], v[2:3], v[4:5] op_sel_hi:[1,0]
	v_pk_fma_f32 v[0:1], v[98:99], v[0:1], v[102:103]
	v_pk_fma_f32 v[2:3], v[100:101], v[2:3], v[104:105]
	v_mul_f32_e32 v4, 0xbfb8aa3b, v0
	v_mul_f32_e32 v5, 0xbfb8aa3b, v1
	v_mul_f32_e32 v6, 0xbfb8aa3b, v2
	v_mul_f32_e32 v7, 0xbfb8aa3b, v3
	v_exp_f32_e32 v4, v4
	v_exp_f32_e32 v5, v5
	v_exp_f32_e32 v6, v6
	v_exp_f32_e32 v7, v7
	v_add_f32_e32 v4, 1.0, v4
	v_add_f32_e32 v5, 1.0, v5
	v_add_f32_e32 v6, 1.0, v6
	v_add_f32_e32 v7, 1.0, v7
	v_rcp_f32_e32 v4, v4
	v_rcp_f32_e32 v5, v5
	v_rcp_f32_e32 v6, v6
	v_rcp_f32_e32 v7, v7
	v_pk_mul_f32 v[0:1], v[0:1], v[4:5]
	s_nop 0
	v_cvt_pk_bf16_f32 v0, v0, v1
	v_pk_mul_f32 v[2:3], v[2:3], v[6:7]
	s_nop 0
	v_cvt_pk_bf16_f32 v1, v2, v3
	v_add_u32_e32 v2, s21, v176
	ds_write_b64 v2, v[0:1]
	v_add_u32_e32 v0, s22, v169
	ds_read_b128 v[0:3], v0
	s_waitcnt lgkmcnt(0)
	v_mov_b32_e32 v4, v1
	v_mov_b32_e32 v5, v2
	v_mov_b32_e32 v6, v0
	v_mov_b32_e32 v7, v3
	v_pk_add_f32 v[4:5], v[4:5], v[6:7]
	s_nop 0
	v_add_f32_e32 v4, v4, v5
	s_nop 1
	v_add_f32_dpp v4, v4, v4 quad_perm:[1,0,3,2] row_mask:0xf bank_mask:0xf
	s_nop 1
	v_add_f32_dpp v4, v4, v4 quad_perm:[2,3,0,1] row_mask:0xf bank_mask:0xf
	s_nop 1
	v_add_f32_dpp v4, v4, v4 row_half_mirror row_mask:0xf bank_mask:0xf
	s_nop 1
	v_add_f32_dpp v4, v4, v4 row_mirror row_mask:0xf bank_mask:0xf
	s_nop 1
	v_add_f32_dpp v4, v4, v4 row_bcast:15 row_mask:0xa bank_mask:0xf
	s_nop 1
	v_add_f32_dpp v4, v4, v4 row_bcast:31 row_mask:0xc bank_mask:0xf
	s_nop 1
	v_readlane_b32 s101, v4, 63
	s_nop 1
	v_mov_b32_e32 v4, s101
	v_fmamk_f32 v1, v4, 0xbb800000, v1
	v_fmamk_f32 v0, v4, 0xbb800000, v0
	v_fmamk_f32 v3, v4, 0xbb800000, v3
	v_fmac_f32_e32 v2, 0xbb800000, v4
	v_pk_mul_f32 v[4:5], v[2:3], v[2:3]
	v_pk_mul_f32 v[6:7], v[0:1], v[0:1]
	s_nop 0
	v_pk_mov_b32 v[8:9], v[6:7], v[4:5] op_sel:[1,0]
	v_mov_b32_e32 v7, v5
	v_pk_add_f32 v[4:5], v[8:9], v[6:7]
	s_nop 0
	v_add_f32_e32 v4, v4, v5
	s_nop 1
	v_add_f32_dpp v4, v4, v4 quad_perm:[1,0,3,2] row_mask:0xf bank_mask:0xf
	s_nop 1
	v_add_f32_dpp v4, v4, v4 quad_perm:[2,3,0,1] row_mask:0xf bank_mask:0xf
	s_nop 1
	v_add_f32_dpp v4, v4, v4 row_half_mirror row_mask:0xf bank_mask:0xf
	s_nop 1
	v_add_f32_dpp v4, v4, v4 row_mirror row_mask:0xf bank_mask:0xf
	s_nop 1
	v_add_f32_dpp v4, v4, v4 row_bcast:15 row_mask:0xa bank_mask:0xf
	s_nop 1
	v_add_f32_dpp v4, v4, v4 row_bcast:31 row_mask:0xc bank_mask:0xf
	s_nop 1
	v_readlane_b32 s101, v4, 63
	s_nop 1
	v_mov_b32_e32 v4, s101
	v_fmamk_f32 v4, v4, 0x3b800000, v210
	v_rsq_f32_e32 v4, v4
	s_nop 0
	v_pk_mul_f32 v[0:1], v[0:1], v[4:5] op_sel_hi:[1,0]
	v_pk_mul_f32 v[2:3], v[2:3], v[4:5] op_sel_hi:[1,0]
	v_pk_fma_f32 v[0:1], v[98:99], v[0:1], v[102:103]
	v_pk_fma_f32 v[2:3], v[100:101], v[2:3], v[104:105]
	v_mul_f32_e32 v4, 0xbfb8aa3b, v0
	v_mul_f32_e32 v5, 0xbfb8aa3b, v1
	v_mul_f32_e32 v6, 0xbfb8aa3b, v2
	v_mul_f32_e32 v7, 0xbfb8aa3b, v3
	v_exp_f32_e32 v4, v4
	v_exp_f32_e32 v5, v5
	v_exp_f32_e32 v6, v6
	v_exp_f32_e32 v7, v7
	v_add_f32_e32 v4, 1.0, v4
	v_add_f32_e32 v5, 1.0, v5
	v_add_f32_e32 v6, 1.0, v6
	v_add_f32_e32 v7, 1.0, v7
	v_rcp_f32_e32 v4, v4
	v_rcp_f32_e32 v5, v5
	v_rcp_f32_e32 v6, v6
	v_rcp_f32_e32 v7, v7
	v_pk_mul_f32 v[0:1], v[0:1], v[4:5]
	s_nop 0
	v_cvt_pk_bf16_f32 v4, v0, v1
	v_pk_mul_f32 v[2:3], v[2:3], v[6:7]
	v_add_u32_e32 v0, s23, v176
	v_cvt_pk_bf16_f32 v5, v2, v3
	ds_write_b64 v0, v[4:5]
	v_add_u32_e32 v1, s24, v169
	ds_read_b128 v[2:5], v1
	s_waitcnt lgkmcnt(0)
; #define LAS __attribute__((address_space(3)))
; __device__ __forceinline__ unsigned pk2(float lo, float hi) { const f32x2_t v = {lo, hi}; const bf16x2_t b = __builtin_convertvector(v, bf16x2_t); return __builtin_bit_cast(unsigned, b); }
; __device__ __forceinline__ float sigmoidf_(float x) { return __builtin_amdgcn_rcpf(1.0f + __builtin_amdgcn_exp2f(-1.4426950408889634f * x)); }
; __device__ __forceinline__ float wave_sum(float v) {
; #pragma unroll
;     for (int o = 1; o < 64; o <<= 1) v += __shfl_xor(v, o);
;     return v;
; __device__ __forceinline__ void conv_phase(LAS unsigned char* lds, const bf16* proj, bf16* mix, const float* cw, const float* cb, const float* lng, const float* lnb, const bf16* pwT, int G, int bid) {
;     ...
;         for (int tt = 0; tt < 8; ++tt) { const int tk = 8 * wid + tt; const f32x4 v = *(const LAS f32x4*)(hb + tk * 256 + 4 * lane);
;             const float mean = wave_sum((v[0] + v[1]) + (v[2] + v[3])) * (1.0f / 256.0f); const f32x4 d = v - mean;
;             const float var = wave_sum((d[0] * d[0] + d[1] * d[1]) + (d[2] * d[2] + d[3] * d[3])) * (1.0f / 256.0f); const float rstd = __builtin_amdgcn_rsqf(var + 1e-5f);
;             f32x4 y = d * rstd * gg + bb;
; #pragma unroll
;             for (int i = 0; i < 4; ++i) y[i] = y[i] * sigmoidf_(y[i]);
;             u32x2 o; o.x = pk2(y[0], y[1]); o.y = pk2(y[2], y[3]); *(LAS u32x2*)(ab + tk * CV_APITCH + lane * 8) = o; }
	v_mov_b32_e32 v6, v3
	v_mov_b32_e32 v7, v4
	v_mov_b32_e32 v8, v2
	v_mov_b32_e32 v9, v5
	v_pk_add_f32 v[6:7], v[6:7], v[8:9]
	s_nop 0
	v_add_f32_e32 v1, v6, v7
	s_nop 1
	v_add_f32_dpp v1, v1, v1 quad_perm:[1,0,3,2] row_mask:0xf bank_mask:0xf
	s_nop 1
	v_add_f32_dpp v1, v1, v1 quad_perm:[2,3,0,1] row_mask:0xf bank_mask:0xf
	s_nop 1
	v_add_f32_dpp v1, v1, v1 row_half_mirror row_mask:0xf bank_mask:0xf
	s_nop 1
	v_add_f32_dpp v1, v1, v1 row_mirror row_mask:0xf bank_mask:0xf
	s_nop 1
	v_add_f32_dpp v1, v1, v1 row_bcast:15 row_mask:0xa bank_mask:0xf
	s_nop 1
	v_add_f32_dpp v1, v1, v1 row_bcast:31 row_mask:0xc bank_mask:0xf
	s_nop 1
	v_readlane_b32 s101, v1, 63
	s_nop 1
	v_mov_b32_e32 v1, s101
	v_fmamk_f32 v3, v1, 0xbb800000, v3
	v_fmamk_f32 v2, v1, 0xbb800000, v2
	v_fmamk_f32 v5, v1, 0xbb800000, v5
	v_fmac_f32_e32 v4, 0xbb800000, v1
	v_pk_mul_f32 v[6:7], v[4:5], v[4:5]
	v_pk_mul_f32 v[8:9], v[2:3], v[2:3]
	s_nop 0
	v_pk_mov_b32 v[10:11], v[8:9], v[6:7] op_sel:[1,0]
	v_mov_b32_e32 v9, v7
	v_pk_add_f32 v[6:7], v[10:11], v[8:9]
	s_nop 0
	v_add_f32_e32 v1, v6, v7
	s_nop 1
	v_add_f32_dpp v1, v1, v1 quad_perm:[1,0,3,2] row_mask:0xf bank_mask:0xf
	s_nop 1
	v_add_f32_dpp v1, v1, v1 quad_perm:[2,3,0,1] row_mask:0xf bank_mask:0xf
	s_nop 1
	v_add_f32_dpp v1, v1, v1 row_half_mirror row_mask:0xf bank_mask:0xf
	s_nop 1
	v_add_f32_dpp v1, v1, v1 row_mirror row_mask:0xf bank_mask:0xf
	s_nop 1
	v_add_f32_dpp v1, v1, v1 row_bcast:15 row_mask:0xa bank_mask:0xf
	s_nop 1
	v_add_f32_dpp v1, v1, v1 row_bcast:31 row_mask:0xc bank_mask:0xf
	s_nop 1
	v_readlane_b32 s101, v1, 63
	s_nop 1
	v_mov_b32_e32 v1, s101
	v_fmamk_f32 v1, v1, 0x3b800000, v210
	v_rsq_f32_e32 v6, v1
	s_nop 0
	v_pk_mul_f32 v[2:3], v[2:3], v[6:7] op_sel_hi:[1,0]
	s_nop 0
	v_pk_fma_f32 v[2:3], v[98:99], v[2:3], v[102:103]
	v_pk_mul_f32 v[4:5], v[4:5], v[6:7] op_sel_hi:[1,0]
	v_mul_f32_e32 v1, 0xbfb8aa3b, v2
	v_exp_f32_e32 v1, v1
	v_mul_f32_e32 v6, 0xbfb8aa3b, v3
	v_exp_f32_e32 v7, v6
	v_pk_fma_f32 v[4:5], v[100:101], v[4:5], v[104:105]
	v_add_f32_e32 v1, 1.0, v1
	v_rcp_f32_e32 v6, v1
	v_add_f32_e32 v1, 1.0, v7
	v_mul_f32_e32 v7, 0xbfb8aa3b, v4
	v_exp_f32_e32 v8, v7
	v_mul_f32_e32 v7, 0xbfb8aa3b, v5
	v_exp_f32_e32 v9, v7
	v_rcp_f32_e32 v7, v1
	v_add_f32_e32 v1, 1.0, v8
	v_rcp_f32_e32 v8, v1
	v_add_f32_e32 v1, 1.0, v9
	v_rcp_f32_e32 v9, v1
	v_pk_mul_f32 v[2:3], v[2:3], v[6:7]
	v_add_u32_e32 v1, s25, v169
	v_cvt_pk_bf16_f32 v2, v2, v3
	v_pk_mul_f32 v[4:5], v[4:5], v[8:9]
	s_nop 0
	v_cvt_pk_bf16_f32 v3, v4, v5
	ds_write_b64 v0, v[2:3] offset:528
	ds_read_b128 v[2:5], v1
	s_waitcnt lgkmcnt(0)
	v_mov_b32_e32 v6, v3
	v_mov_b32_e32 v7, v4
	v_mov_b32_e32 v8, v2
	v_mov_b32_e32 v9, v5
	v_pk_add_f32 v[6:7], v[6:7], v[8:9]
	s_nop 0
	v_add_f32_e32 v1, v6, v7
	s_nop 1
	v_add_f32_dpp v1, v1, v1 quad_perm:[1,0,3,2] row_mask:0xf bank_mask:0xf
	s_nop 1
	v_add_f32_dpp v1, v1, v1 quad_perm:[2,3,0,1] row_mask:0xf bank_mask:0xf
	s_nop 1
	v_add_f32_dpp v1, v1, v1 row_half_mirror row_mask:0xf bank_mask:0xf
	s_nop 1
	v_add_f32_dpp v1, v1, v1 row_mirror row_mask:0xf bank_mask:0xf
	s_nop 1
	v_add_f32_dpp v1, v1, v1 row_bcast:15 row_mask:0xa bank_mask:0xf
	s_nop 1
	v_add_f32_dpp v1, v1, v1 row_bcast:31 row_mask:0xc bank_mask:0xf
	s_nop 1
	v_readlane_b32 s101, v1, 63
	s_nop 1
	v_mov_b32_e32 v1, s101
	v_fmamk_f32 v3, v1, 0xbb800000, v3
	v_fmamk_f32 v2, v1, 0xbb800000, v2
	v_fmamk_f32 v5, v1, 0xbb800000, v5
	v_fmac_f32_e32 v4, 0xbb800000, v1
	v_pk_mul_f32 v[6:7], v[4:5], v[4:5]
	v_pk_mul_f32 v[8:9], v[2:3], v[2:3]
	s_nop 0
	v_pk_mov_b32 v[10:11], v[8:9], v[6:7] op_sel:[1,0]
	v_mov_b32_e32 v9, v7
	v_pk_add_f32 v[6:7], v[10:11], v[8:9]
	s_nop 0
	v_add_f32_e32 v1, v6, v7
	s_nop 1
	v_add_f32_dpp v1, v1, v1 quad_perm:[1,0,3,2] row_mask:0xf bank_mask:0xf
	s_nop 1
	v_add_f32_dpp v1, v1, v1 quad_perm:[2,3,0,1] row_mask:0xf bank_mask:0xf
	s_nop 1
	v_add_f32_dpp v1, v1, v1 row_half_mirror row_mask:0xf bank_mask:0xf
	s_nop 1
	v_add_f32_dpp v1, v1, v1 row_mirror row_mask:0xf bank_mask:0xf
	s_nop 1
	v_add_f32_dpp v1, v1, v1 row_bcast:15 row_mask:0xa bank_mask:0xf
	s_nop 1
	v_add_f32_dpp v1, v1, v1 row_bcast:31 row_mask:0xc bank_mask:0xf
	s_nop 1
	v_readlane_b32 s101, v1, 63
	s_nop 1
	v_mov_b32_e32 v1, s101
	v_fmamk_f32 v1, v1, 0x3b800000, v210
	v_rsq_f32_e32 v6, v1
	s_nop 0
	v_pk_mul_f32 v[2:3], v[2:3], v[6:7] op_sel_hi:[1,0]
	s_nop 0
	v_pk_fma_f32 v[2:3], v[98:99], v[2:3], v[102:103]
	v_pk_mul_f32 v[4:5], v[4:5], v[6:7] op_sel_hi:[1,0]
	v_mul_f32_e32 v1, 0xbfb8aa3b, v2
	v_exp_f32_e32 v1, v1
	v_mul_f32_e32 v6, 0xbfb8aa3b, v3
	v_exp_f32_e32 v7, v6
	v_pk_fma_f32 v[4:5], v[100:101], v[4:5], v[104:105]
	v_add_f32_e32 v1, 1.0, v1
	v_rcp_f32_e32 v6, v1
	v_add_f32_e32 v1, 1.0, v7
	v_mul_f32_e32 v7, 0xbfb8aa3b, v4
	v_exp_f32_e32 v8, v7
	v_mul_f32_e32 v7, 0xbfb8aa3b, v5
	v_exp_f32_e32 v9, v7
	v_rcp_f32_e32 v7, v1
	v_add_f32_e32 v1, 1.0, v8
	v_rcp_f32_e32 v8, v1
	v_add_f32_e32 v1, 1.0, v9
	v_rcp_f32_e32 v9, v1
	v_pk_mul_f32 v[2:3], v[2:3], v[6:7]
	v_add_u32_e32 v1, s26, v169
	v_cvt_pk_bf16_f32 v2, v2, v3
	v_pk_mul_f32 v[4:5], v[4:5], v[8:9]
	s_nop 0
	v_cvt_pk_bf16_f32 v3, v4, v5
	ds_write_b64 v0, v[2:3] offset:1056
	ds_read_b128 v[2:5], v1
	s_waitcnt lgkmcnt(0)
; #define LAS __attribute__((address_space(3)))
; __device__ __forceinline__ unsigned pk2(float lo, float hi) { const f32x2_t v = {lo, hi}; const bf16x2_t b = __builtin_convertvector(v, bf16x2_t); return __builtin_bit_cast(unsigned, b); }
; __device__ __forceinline__ float sigmoidf_(float x) { return __builtin_amdgcn_rcpf(1.0f + __builtin_amdgcn_exp2f(-1.4426950408889634f * x)); }
; __device__ __forceinline__ float wave_sum(float v) {
; #pragma unroll
;     for (int o = 1; o < 64; o <<= 1) v += __shfl_xor(v, o);
;     return v;
; __device__ __forceinline__ void conv_phase(LAS unsigned char* lds, const bf16* proj, bf16* mix, const float* cw, const float* cb, const float* lng, const float* lnb, const bf16* pwT, int G, int bid) {
;     ...
;         for (int tt = 0; tt < 8; ++tt) { const int tk = 8 * wid + tt; const f32x4 v = *(const LAS f32x4*)(hb + tk * 256 + 4 * lane);
;             const float mean = wave_sum((v[0] + v[1]) + (v[2] + v[3])) * (1.0f / 256.0f); const f32x4 d = v - mean;
;             const float var = wave_sum((d[0] * d[0] + d[1] * d[1]) + (d[2] * d[2] + d[3] * d[3])) * (1.0f / 256.0f); const float rstd = __builtin_amdgcn_rsqf(var + 1e-5f);
;             f32x4 y = d * rstd * gg + bb;
; #pragma unroll
;             for (int i = 0; i < 4; ++i) y[i] = y[i] * sigmoidf_(y[i]);
;             u32x2 o; o.x = pk2(y[0], y[1]); o.y = pk2(y[2], y[3]); *(LAS u32x2*)(ab + tk * CV_APITCH + lane * 8) = o; }
	v_mov_b32_e32 v6, v3
	v_mov_b32_e32 v7, v4
	v_mov_b32_e32 v8, v2
	v_mov_b32_e32 v9, v5
	v_pk_add_f32 v[6:7], v[6:7], v[8:9]
	s_nop 0
	v_add_f32_e32 v1, v6, v7
	s_nop 1
	v_add_f32_dpp v1, v1, v1 quad_perm:[1,0,3,2] row_mask:0xf bank_mask:0xf
	s_nop 1
	v_add_f32_dpp v1, v1, v1 quad_perm:[2,3,0,1] row_mask:0xf bank_mask:0xf
	s_nop 1
	v_add_f32_dpp v1, v1, v1 row_half_mirror row_mask:0xf bank_mask:0xf
	s_nop 1
	v_add_f32_dpp v1, v1, v1 row_mirror row_mask:0xf bank_mask:0xf
	s_nop 1
	v_add_f32_dpp v1, v1, v1 row_bcast:15 row_mask:0xa bank_mask:0xf
	s_nop 1
	v_add_f32_dpp v1, v1, v1 row_bcast:31 row_mask:0xc bank_mask:0xf
	s_nop 1
	v_readlane_b32 s101, v1, 63
	s_nop 1
	v_mov_b32_e32 v1, s101
	v_fmamk_f32 v3, v1, 0xbb800000, v3
	v_fmamk_f32 v2, v1, 0xbb800000, v2
	v_fmamk_f32 v5, v1, 0xbb800000, v5
	v_fmac_f32_e32 v4, 0xbb800000, v1
	v_pk_mul_f32 v[6:7], v[4:5], v[4:5]
	v_pk_mul_f32 v[8:9], v[2:3], v[2:3]
	s_nop 0
	v_pk_mov_b32 v[10:11], v[8:9], v[6:7] op_sel:[1,0]
	v_mov_b32_e32 v9, v7
	v_pk_add_f32 v[6:7], v[10:11], v[8:9]
	s_nop 0
	v_add_f32_e32 v1, v6, v7
	s_nop 1
	v_add_f32_dpp v1, v1, v1 quad_perm:[1,0,3,2] row_mask:0xf bank_mask:0xf
	s_nop 1
	v_add_f32_dpp v1, v1, v1 quad_perm:[2,3,0,1] row_mask:0xf bank_mask:0xf
	s_nop 1
	v_add_f32_dpp v1, v1, v1 row_half_mirror row_mask:0xf bank_mask:0xf
	s_nop 1
	v_add_f32_dpp v1, v1, v1 row_mirror row_mask:0xf bank_mask:0xf
	s_nop 1
	v_add_f32_dpp v1, v1, v1 row_bcast:15 row_mask:0xa bank_mask:0xf
	s_nop 1
	v_add_f32_dpp v1, v1, v1 row_bcast:31 row_mask:0xc bank_mask:0xf
	s_nop 1
	v_readlane_b32 s101, v1, 63
	s_nop 1
	v_mov_b32_e32 v1, s101
	v_fmamk_f32 v1, v1, 0x3b800000, v210
	v_rsq_f32_e32 v6, v1
	s_nop 0
	v_pk_mul_f32 v[2:3], v[2:3], v[6:7] op_sel_hi:[1,0]
	s_nop 0
	v_pk_fma_f32 v[2:3], v[98:99], v[2:3], v[102:103]
	v_pk_mul_f32 v[4:5], v[4:5], v[6:7] op_sel_hi:[1,0]
	v_mul_f32_e32 v1, 0xbfb8aa3b, v2
	v_exp_f32_e32 v1, v1
	v_mul_f32_e32 v6, 0xbfb8aa3b, v3
	v_exp_f32_e32 v7, v6
	v_pk_fma_f32 v[4:5], v[100:101], v[4:5], v[104:105]
	v_add_f32_e32 v1, 1.0, v1
	v_rcp_f32_e32 v6, v1
	v_add_f32_e32 v1, 1.0, v7
	v_mul_f32_e32 v7, 0xbfb8aa3b, v4
	v_exp_f32_e32 v8, v7
	v_mul_f32_e32 v7, 0xbfb8aa3b, v5
	v_exp_f32_e32 v9, v7
	v_rcp_f32_e32 v7, v1
	v_add_f32_e32 v1, 1.0, v8
	v_rcp_f32_e32 v8, v1
	v_add_f32_e32 v1, 1.0, v9
	v_rcp_f32_e32 v9, v1
	v_pk_mul_f32 v[2:3], v[2:3], v[6:7]
	v_add_u32_e32 v1, s27, v169
	v_cvt_pk_bf16_f32 v2, v2, v3
	v_pk_mul_f32 v[4:5], v[4:5], v[8:9]
	s_nop 0
	v_cvt_pk_bf16_f32 v3, v4, v5
	ds_write_b64 v0, v[2:3] offset:1584
	ds_read_b128 v[2:5], v1
	s_waitcnt lgkmcnt(0)
	v_mov_b32_e32 v6, v3
	v_mov_b32_e32 v7, v4
	v_mov_b32_e32 v8, v2
	v_mov_b32_e32 v9, v5
	v_pk_add_f32 v[6:7], v[6:7], v[8:9]
	s_nop 0
	v_add_f32_e32 v1, v6, v7
	s_nop 1
	v_add_f32_dpp v1, v1, v1 quad_perm:[1,0,3,2] row_mask:0xf bank_mask:0xf
	s_nop 1
	v_add_f32_dpp v1, v1, v1 quad_perm:[2,3,0,1] row_mask:0xf bank_mask:0xf
	s_nop 1
	v_add_f32_dpp v1, v1, v1 row_half_mirror row_mask:0xf bank_mask:0xf
	s_nop 1
	v_add_f32_dpp v1, v1, v1 row_mirror row_mask:0xf bank_mask:0xf
	s_nop 1
	v_add_f32_dpp v1, v1, v1 row_bcast:15 row_mask:0xa bank_mask:0xf
	s_nop 1
	v_add_f32_dpp v1, v1, v1 row_bcast:31 row_mask:0xc bank_mask:0xf
	s_nop 1
	v_readlane_b32 s101, v1, 63
	s_nop 1
	v_mov_b32_e32 v1, s101
	v_fmamk_f32 v3, v1, 0xbb800000, v3
	v_fmamk_f32 v2, v1, 0xbb800000, v2
	v_fmamk_f32 v5, v1, 0xbb800000, v5
	v_fmac_f32_e32 v4, 0xbb800000, v1
	v_pk_mul_f32 v[6:7], v[4:5], v[4:5]
	v_pk_mul_f32 v[8:9], v[2:3], v[2:3]
	s_nop 0
	v_pk_mov_b32 v[10:11], v[8:9], v[6:7] op_sel:[1,0]
	v_mov_b32_e32 v9, v7
	v_pk_add_f32 v[6:7], v[10:11], v[8:9]
	s_nop 0
	v_add_f32_e32 v1, v6, v7
	s_nop 1
	v_add_f32_dpp v1, v1, v1 quad_perm:[1,0,3,2] row_mask:0xf bank_mask:0xf
	s_nop 1
	v_add_f32_dpp v1, v1, v1 quad_perm:[2,3,0,1] row_mask:0xf bank_mask:0xf
	s_nop 1
	v_add_f32_dpp v1, v1, v1 row_half_mirror row_mask:0xf bank_mask:0xf
	s_nop 1
	v_add_f32_dpp v1, v1, v1 row_mirror row_mask:0xf bank_mask:0xf
	s_nop 1
	v_add_f32_dpp v1, v1, v1 row_bcast:15 row_mask:0xa bank_mask:0xf
	s_nop 1
	v_add_f32_dpp v1, v1, v1 row_bcast:31 row_mask:0xc bank_mask:0xf
	s_nop 1
	v_readlane_b32 s101, v1, 63
	s_nop 1
	v_mov_b32_e32 v1, s101
	v_fmamk_f32 v1, v1, 0x3b800000, v210
	v_rsq_f32_e32 v6, v1
	s_nop 0
	v_pk_mul_f32 v[2:3], v[2:3], v[6:7] op_sel_hi:[1,0]
	s_nop 0
	v_pk_fma_f32 v[2:3], v[98:99], v[2:3], v[102:103]
	v_pk_mul_f32 v[4:5], v[4:5], v[6:7] op_sel_hi:[1,0]
	v_mul_f32_e32 v1, 0xbfb8aa3b, v2
	v_exp_f32_e32 v1, v1
	v_mul_f32_e32 v6, 0xbfb8aa3b, v3
	v_exp_f32_e32 v7, v6
	v_pk_fma_f32 v[4:5], v[100:101], v[4:5], v[104:105]
	v_add_f32_e32 v1, 1.0, v1
	v_rcp_f32_e32 v6, v1
	v_add_f32_e32 v1, 1.0, v7
	v_mul_f32_e32 v7, 0xbfb8aa3b, v4
	v_exp_f32_e32 v8, v7
	v_mul_f32_e32 v7, 0xbfb8aa3b, v5
	v_exp_f32_e32 v9, v7
	v_rcp_f32_e32 v7, v1
	v_add_f32_e32 v1, 1.0, v8
	v_rcp_f32_e32 v8, v1
	v_add_f32_e32 v1, 1.0, v9
	v_rcp_f32_e32 v9, v1
	v_pk_mul_f32 v[2:3], v[2:3], v[6:7]
	v_add_u32_e32 v1, s28, v169
	v_cvt_pk_bf16_f32 v2, v2, v3
	v_pk_mul_f32 v[4:5], v[4:5], v[8:9]
	s_nop 0
	v_cvt_pk_bf16_f32 v3, v4, v5
	ds_write_b64 v0, v[2:3] offset:2112
	ds_read_b128 v[2:5], v1
	s_waitcnt lgkmcnt(0)
; #define LAS __attribute__((address_space(3)))
; __device__ __forceinline__ unsigned pk2(float lo, float hi) { const f32x2_t v = {lo, hi}; const bf16x2_t b = __builtin_convertvector(v, bf16x2_t); return __builtin_bit_cast(unsigned, b); }
; __device__ __forceinline__ float sigmoidf_(float x) { return __builtin_amdgcn_rcpf(1.0f + __builtin_amdgcn_exp2f(-1.4426950408889634f * x)); }
; __device__ __forceinline__ float wave_sum(float v) {
; #pragma unroll
;     for (int o = 1; o < 64; o <<= 1) v += __shfl_xor(v, o);
;     return v;
; __device__ __forceinline__ void conv_phase(LAS unsigned char* lds, const bf16* proj, bf16* mix, const float* cw, const float* cb, const float* lng, const float* lnb, const bf16* pwT, int G, int bid) {
;     ...
;         for (int tt = 0; tt < 8; ++tt) { const int tk = 8 * wid + tt; const f32x4 v = *(const LAS f32x4*)(hb + tk * 256 + 4 * lane);
;             const float mean = wave_sum((v[0] + v[1]) + (v[2] + v[3])) * (1.0f / 256.0f); const f32x4 d = v - mean;
;             const float var = wave_sum((d[0] * d[0] + d[1] * d[1]) + (d[2] * d[2] + d[3] * d[3])) * (1.0f / 256.0f); const float rstd = __builtin_amdgcn_rsqf(var + 1e-5f);
;             f32x4 y = d * rstd * gg + bb;
; #pragma unroll
;             for (int i = 0; i < 4; ++i) y[i] = y[i] * sigmoidf_(y[i]);
;             u32x2 o; o.x = pk2(y[0], y[1]); o.y = pk2(y[2], y[3]); *(LAS u32x2*)(ab + tk * CV_APITCH + lane * 8) = o; }
	v_mov_b32_e32 v6, v3
	v_mov_b32_e32 v7, v4
	v_mov_b32_e32 v8, v2
	v_mov_b32_e32 v9, v5
	v_pk_add_f32 v[6:7], v[6:7], v[8:9]
	s_nop 0
	v_add_f32_e32 v1, v6, v7
	s_nop 1
	v_add_f32_dpp v1, v1, v1 quad_perm:[1,0,3,2] row_mask:0xf bank_mask:0xf
	s_nop 1
	v_add_f32_dpp v1, v1, v1 quad_perm:[2,3,0,1] row_mask:0xf bank_mask:0xf
	s_nop 1
	v_add_f32_dpp v1, v1, v1 row_half_mirror row_mask:0xf bank_mask:0xf
	s_nop 1
	v_add_f32_dpp v1, v1, v1 row_mirror row_mask:0xf bank_mask:0xf
	s_nop 1
	v_add_f32_dpp v1, v1, v1 row_bcast:15 row_mask:0xa bank_mask:0xf
	s_nop 1
	v_add_f32_dpp v1, v1, v1 row_bcast:31 row_mask:0xc bank_mask:0xf
	s_nop 1
	v_readlane_b32 s101, v1, 63
	s_nop 1
	v_mov_b32_e32 v1, s101
	v_fmamk_f32 v3, v1, 0xbb800000, v3
	v_fmamk_f32 v2, v1, 0xbb800000, v2
	v_fmamk_f32 v5, v1, 0xbb800000, v5
	v_fmac_f32_e32 v4, 0xbb800000, v1
	v_pk_mul_f32 v[6:7], v[4:5], v[4:5]
	v_pk_mul_f32 v[8:9], v[2:3], v[2:3]
	s_nop 0
	v_pk_mov_b32 v[10:11], v[8:9], v[6:7] op_sel:[1,0]
	v_mov_b32_e32 v9, v7
	v_pk_add_f32 v[6:7], v[10:11], v[8:9]
	s_nop 0
	v_add_f32_e32 v1, v6, v7
	s_nop 1
	v_add_f32_dpp v1, v1, v1 quad_perm:[1,0,3,2] row_mask:0xf bank_mask:0xf
	s_nop 1
	v_add_f32_dpp v1, v1, v1 quad_perm:[2,3,0,1] row_mask:0xf bank_mask:0xf
	s_nop 1
	v_add_f32_dpp v1, v1, v1 row_half_mirror row_mask:0xf bank_mask:0xf
	s_nop 1
	v_add_f32_dpp v1, v1, v1 row_mirror row_mask:0xf bank_mask:0xf
	s_nop 1
	v_add_f32_dpp v1, v1, v1 row_bcast:15 row_mask:0xa bank_mask:0xf
	s_nop 1
	v_add_f32_dpp v1, v1, v1 row_bcast:31 row_mask:0xc bank_mask:0xf
	s_nop 1
	v_readlane_b32 s101, v1, 63
	s_nop 1
	v_mov_b32_e32 v1, s101
	v_fmamk_f32 v1, v1, 0x3b800000, v210
	v_rsq_f32_e32 v6, v1
	s_nop 0
	v_pk_mul_f32 v[2:3], v[2:3], v[6:7] op_sel_hi:[1,0]
	s_nop 0
	v_pk_fma_f32 v[2:3], v[98:99], v[2:3], v[102:103]
	v_pk_mul_f32 v[4:5], v[4:5], v[6:7] op_sel_hi:[1,0]
	v_mul_f32_e32 v1, 0xbfb8aa3b, v2
	v_exp_f32_e32 v1, v1
	v_mul_f32_e32 v6, 0xbfb8aa3b, v3
	v_exp_f32_e32 v7, v6
	v_pk_fma_f32 v[4:5], v[100:101], v[4:5], v[104:105]
	v_add_f32_e32 v1, 1.0, v1
	v_rcp_f32_e32 v6, v1
	v_add_f32_e32 v1, 1.0, v7
	v_mul_f32_e32 v7, 0xbfb8aa3b, v4
	v_exp_f32_e32 v8, v7
	v_mul_f32_e32 v7, 0xbfb8aa3b, v5
	v_exp_f32_e32 v9, v7
	v_rcp_f32_e32 v7, v1
	v_add_f32_e32 v1, 1.0, v8
	v_rcp_f32_e32 v8, v1
	v_add_f32_e32 v1, 1.0, v9
	v_rcp_f32_e32 v9, v1
	v_pk_mul_f32 v[2:3], v[2:3], v[6:7]
	v_add_u32_e32 v1, s29, v169
	v_cvt_pk_bf16_f32 v2, v2, v3
	v_pk_mul_f32 v[4:5], v[4:5], v[8:9]
	s_nop 0
	v_cvt_pk_bf16_f32 v3, v4, v5
	ds_write_b64 v0, v[2:3] offset:2640
	ds_read_b128 v[2:5], v1
	s_waitcnt lgkmcnt(0)
	v_mov_b32_e32 v6, v3
	v_mov_b32_e32 v7, v4
	v_mov_b32_e32 v8, v2
	v_mov_b32_e32 v9, v5
	v_pk_add_f32 v[6:7], v[6:7], v[8:9]
	s_nop 0
	v_add_f32_e32 v1, v6, v7
	s_nop 1
	v_add_f32_dpp v1, v1, v1 quad_perm:[1,0,3,2] row_mask:0xf bank_mask:0xf
	s_nop 1
	v_add_f32_dpp v1, v1, v1 quad_perm:[2,3,0,1] row_mask:0xf bank_mask:0xf
	s_nop 1
	v_add_f32_dpp v1, v1, v1 row_half_mirror row_mask:0xf bank_mask:0xf
	s_nop 1
	v_add_f32_dpp v1, v1, v1 row_mirror row_mask:0xf bank_mask:0xf
	s_nop 1
	v_add_f32_dpp v1, v1, v1 row_bcast:15 row_mask:0xa bank_mask:0xf
	s_nop 1
	v_add_f32_dpp v1, v1, v1 row_bcast:31 row_mask:0xc bank_mask:0xf
	s_nop 1
	v_readlane_b32 s101, v1, 63
	s_nop 1
	v_mov_b32_e32 v1, s101
	v_fmamk_f32 v3, v1, 0xbb800000, v3
	v_fmamk_f32 v2, v1, 0xbb800000, v2
	v_fmamk_f32 v5, v1, 0xbb800000, v5
	v_fmac_f32_e32 v4, 0xbb800000, v1
	v_pk_mul_f32 v[6:7], v[4:5], v[4:5]
	v_pk_mul_f32 v[8:9], v[2:3], v[2:3]
	s_nop 0
	v_pk_mov_b32 v[10:11], v[8:9], v[6:7] op_sel:[1,0]
	v_mov_b32_e32 v9, v7
	v_pk_add_f32 v[6:7], v[10:11], v[8:9]
	s_nop 0
	v_add_f32_e32 v1, v6, v7
	s_nop 1
	v_add_f32_dpp v1, v1, v1 quad_perm:[1,0,3,2] row_mask:0xf bank_mask:0xf
	s_nop 1
	v_add_f32_dpp v1, v1, v1 quad_perm:[2,3,0,1] row_mask:0xf bank_mask:0xf
	s_nop 1
	v_add_f32_dpp v1, v1, v1 row_half_mirror row_mask:0xf bank_mask:0xf
	s_nop 1
	v_add_f32_dpp v1, v1, v1 row_mirror row_mask:0xf bank_mask:0xf
	s_nop 1
	v_add_f32_dpp v1, v1, v1 row_bcast:15 row_mask:0xa bank_mask:0xf
	s_nop 1
	v_add_f32_dpp v1, v1, v1 row_bcast:31 row_mask:0xc bank_mask:0xf
	s_nop 1
	v_readlane_b32 s101, v1, 63
	s_nop 1
	v_mov_b32_e32 v1, s101
	v_fmamk_f32 v1, v1, 0x3b800000, v210
	v_rsq_f32_e32 v6, v1
	s_nop 0
	v_pk_mul_f32 v[2:3], v[2:3], v[6:7] op_sel_hi:[1,0]
	s_nop 0
	v_pk_fma_f32 v[2:3], v[98:99], v[2:3], v[102:103]
	v_pk_mul_f32 v[4:5], v[4:5], v[6:7] op_sel_hi:[1,0]
	v_mul_f32_e32 v1, 0xbfb8aa3b, v2
	v_exp_f32_e32 v1, v1
	v_mul_f32_e32 v6, 0xbfb8aa3b, v3
	v_exp_f32_e32 v7, v6
	v_pk_fma_f32 v[4:5], v[100:101], v[4:5], v[104:105]
	v_add_f32_e32 v1, 1.0, v1
	v_rcp_f32_e32 v6, v1
	v_add_f32_e32 v1, 1.0, v7
	v_mul_f32_e32 v7, 0xbfb8aa3b, v4
	v_exp_f32_e32 v8, v7
	v_mul_f32_e32 v7, 0xbfb8aa3b, v5
	v_exp_f32_e32 v9, v7
	v_rcp_f32_e32 v7, v1
	v_add_f32_e32 v1, 1.0, v8
	v_rcp_f32_e32 v8, v1
	v_add_f32_e32 v1, 1.0, v9
	v_rcp_f32_e32 v9, v1
	v_pk_mul_f32 v[2:3], v[2:3], v[6:7]
	v_pk_mul_f32 v[4:5], v[4:5], v[8:9]
	v_cvt_pk_bf16_f32 v2, v2, v3
	v_cvt_pk_bf16_f32 v3, v4, v5
	ds_write_b64 v0, v[2:3] offset:3168
	s_waitcnt lgkmcnt(0)
	s_barrier
; #define LAS __attribute__((address_space(3)))
; __device__ __forceinline__ void conv_phase(LAS unsigned char* lds, const bf16* proj, bf16* mix, const float* cw, const float* cb, const float* lng, const float* lnb, const bf16* pwT, int G, int bid) {
;     ...
;         f32x16 a0 = {}, a1 = {};
; #pragma unroll
;         for (int kk = 0; kk < 16; ++kk) {
;             const bf16x8 f0 = *(const LAS bf16x8*)(ab + r32 * CV_APITCH + (16 * kk + 8 * hi) * 2), f1 = *(const LAS bf16x8*)(ab + (r32 + 32) * CV_APITCH + (16 * kk + 8 * hi) * 2);
;             a0 = __builtin_amdgcn_mfma_f32_32x32x16_bf16(f0, pwf[kk], a0, 0, 0, 0); a1 = __builtin_amdgcn_mfma_f32_32x32x16_bf16(f1, pwf[kk], a1, 0, 0, 0);
;         }
	ds_read_b128 v[0:3], v80
	ds_read_b128 v[110:113], v80 offset:32
	s_waitcnt lgkmcnt(1)
	v_mfma_f32_32x32x16_bf16 v[0:15], v[0:3], v[90:93], 0
	ds_read_b128 v[16:19], v80 offset:16896
	ds_read_b128 v[114:117], v80 offset:16928
	s_waitcnt lgkmcnt(1)
	v_mfma_f32_32x32x16_bf16 v[16:31], v[16:19], v[90:93], 0
	v_mfma_f32_32x32x16_bf16 v[0:15], v[110:113], v[32:35], v[0:15]
	s_waitcnt lgkmcnt(0)
	v_mfma_f32_32x32x16_bf16 v[16:31], v[114:117], v[32:35], v[16:31]
	ds_read_b128 v[110:113], v80 offset:64
	ds_read_b128 v[114:117], v80 offset:96
	s_waitcnt lgkmcnt(1)
	v_mfma_f32_32x32x16_bf16 v[0:15], v[110:113], v[36:39], v[0:15]
	ds_read_b128 v[110:113], v80 offset:16960
	ds_read_b128 v[118:121], v80 offset:16992
	s_waitcnt lgkmcnt(1)
	v_mfma_f32_32x32x16_bf16 v[16:31], v[110:113], v[36:39], v[16:31]
	v_mfma_f32_32x32x16_bf16 v[0:15], v[114:117], v[40:43], v[0:15]
	ds_read_b128 v[110:113], v80 offset:128
	ds_read_b128 v[114:117], v80 offset:160
	s_waitcnt lgkmcnt(2)
	v_mfma_f32_32x32x16_bf16 v[16:31], v[118:121], v[40:43], v[16:31]
	s_waitcnt lgkmcnt(1)
	v_mfma_f32_32x32x16_bf16 v[0:15], v[110:113], v[44:47], v[0:15]
	ds_read_b128 v[110:113], v80 offset:17024
	ds_read_b128 v[118:121], v80 offset:17056
	s_waitcnt lgkmcnt(1)
	v_mfma_f32_32x32x16_bf16 v[16:31], v[110:113], v[44:47], v[16:31]
	v_mfma_f32_32x32x16_bf16 v[0:15], v[114:117], v[48:51], v[0:15]
	ds_read_b128 v[110:113], v80 offset:192
	ds_read_b128 v[114:117], v80 offset:224
	s_waitcnt lgkmcnt(2)
	v_mfma_f32_32x32x16_bf16 v[16:31], v[118:121], v[48:51], v[16:31]
	s_waitcnt lgkmcnt(1)
	v_mfma_f32_32x32x16_bf16 v[0:15], v[110:113], v[52:55], v[0:15]
	ds_read_b128 v[110:113], v80 offset:17088
	ds_read_b128 v[118:121], v80 offset:17120
	s_waitcnt lgkmcnt(1)
	v_mfma_f32_32x32x16_bf16 v[16:31], v[110:113], v[52:55], v[16:31]
	v_mfma_f32_32x32x16_bf16 v[0:15], v[114:117], v[56:59], v[0:15]
	ds_read_b128 v[110:113], v80 offset:256
	ds_read_b128 v[114:117], v80 offset:288
	s_waitcnt lgkmcnt(2)
	v_mfma_f32_32x32x16_bf16 v[16:31], v[118:121], v[56:59], v[16:31]
	s_waitcnt lgkmcnt(1)
	v_mfma_f32_32x32x16_bf16 v[0:15], v[110:113], v[60:63], v[0:15]
	ds_read_b128 v[110:113], v80 offset:17152
	ds_read_b128 v[118:121], v80 offset:17184
	s_waitcnt lgkmcnt(1)
	v_mfma_f32_32x32x16_bf16 v[16:31], v[110:113], v[60:63], v[16:31]
	v_mfma_f32_32x32x16_bf16 v[0:15], v[114:117], v[64:67], v[0:15]
	ds_read_b128 v[110:113], v80 offset:320
	ds_read_b128 v[114:117], v80 offset:352
	s_waitcnt lgkmcnt(2)
	v_mfma_f32_32x32x16_bf16 v[16:31], v[118:121], v[64:67], v[16:31]
	s_waitcnt lgkmcnt(1)
	v_mfma_f32_32x32x16_bf16 v[0:15], v[110:113], v[68:71], v[0:15]
	ds_read_b128 v[110:113], v80 offset:17216
	ds_read_b128 v[118:121], v80 offset:17248
	s_waitcnt lgkmcnt(1)
	v_mfma_f32_32x32x16_bf16 v[16:31], v[110:113], v[68:71], v[16:31]
	v_mfma_f32_32x32x16_bf16 v[0:15], v[114:117], v[72:75], v[0:15]
	ds_read_b128 v[110:113], v80 offset:384
	ds_read_b128 v[114:117], v80 offset:416
	s_waitcnt lgkmcnt(2)
	v_mfma_f32_32x32x16_bf16 v[16:31], v[118:121], v[72:75], v[16:31]
	s_waitcnt lgkmcnt(1)
	v_mfma_f32_32x32x16_bf16 v[0:15], v[110:113], v[76:79], v[0:15]
	ds_read_b128 v[110:113], v80 offset:17280
	ds_read_b128 v[118:121], v80 offset:17312
	s_waitcnt lgkmcnt(1)
	v_mfma_f32_32x32x16_bf16 v[16:31], v[110:113], v[76:79], v[16:31]
	v_mfma_f32_32x32x16_bf16 v[0:15], v[114:117], v[82:85], v[0:15]
	ds_read_b128 v[110:113], v80 offset:448
	ds_read_b128 v[114:117], v80 offset:480
	s_waitcnt lgkmcnt(2)
	v_mfma_f32_32x32x16_bf16 v[16:31], v[118:121], v[82:85], v[16:31]
	s_waitcnt lgkmcnt(1)
	v_mfma_f32_32x32x16_bf16 v[0:15], v[110:113], v[86:89], v[0:15]
	ds_read_b128 v[110:113], v80 offset:17344
	ds_read_b128 v[118:121], v80 offset:17376
	s_waitcnt lgkmcnt(1)
	v_mfma_f32_32x32x16_bf16 v[16:31], v[110:113], v[86:89], v[16:31]
	v_lshl_add_u64 v[110:111], v[108:109], 0, s[0:1]
	v_mfma_f32_32x32x16_bf16 v[0:15], v[114:117], v[94:97], v[0:15]
	s_waitcnt lgkmcnt(0)
; __device__ __forceinline__ unsigned pk2(float lo, float hi) { const f32x2_t v = {lo, hi}; const bf16x2_t b = __builtin_convertvector(v, bf16x2_t); return __builtin_bit_cast(unsigned, b); }
; __device__ __forceinline__ int crow(int r, int hi) { return (r & 3) + 8 * (r >> 2) + 4 * hi; }
; __device__ __forceinline__ void conv_phase(LAS unsigned char* lds, const bf16* proj, bf16* mix, const float* cw, const float* cb, const float* lng, const float* lnb, const bf16* pwT, int G, int bid) {
;     ...
;         bf16* Op = mix + (size_t)tok0 * DM + 768 + 32 * wid + r32;
; #pragma unroll
;         for (int r = 0; r < 16; ++r) { Op[(size_t)crow(r, hi) * DM] = (bf16)(pk2(a0[r], 0.f) & 0xffffu); Op[(size_t)(crow(r, hi) + 32) * DM] = (bf16)(pk2(a1[r], 0.f) & 0xffffu); }
	v_mfma_f32_32x32x16_bf16 v[16:31], v[118:121], v[94:97], v[16:31]
	s_nop 9
	v_cvt_pk_bf16_f32 v0, v0, s0
	flat_store_short v[110:111], v0 offset:1536
	v_cvt_pk_bf16_f32 v0, v16, s0
	s_mov_b32 s0, 0x10000
	v_add_co_u32_e32 v112, vcc, s0, v110
	v_cvt_pk_bf16_f32 v2, v2, s0
	s_nop 0
	v_addc_co_u32_e32 v113, vcc, 0, v111, vcc
	flat_store_short v[112:113], v0 offset:1536
	v_cvt_pk_bf16_f32 v0, v1, s0
	flat_store_short v[110:111], v0 offset:3584
	v_cvt_pk_bf16_f32 v0, v17, s0
	flat_store_short v[112:113], v0 offset:3584
	v_add_co_u32_e32 v0, vcc, s89, v110
	s_nop 1
	v_addc_co_u32_e32 v1, vcc, 0, v111, vcc
	flat_store_short v[0:1], v2 offset:1536
	v_cvt_pk_bf16_f32 v2, v18, s0
	s_mov_b32 s0, 0x11000
	v_add_co_u32_e32 v16, vcc, s0, v110
	s_nop 1
	v_addc_co_u32_e32 v17, vcc, 0, v111, vcc
	flat_store_short v[16:17], v2 offset:1536
	v_cvt_pk_bf16_f32 v2, v3, s0
	flat_store_short v[0:1], v2 offset:3584
	v_cvt_pk_bf16_f32 v0, v19, s0
	flat_store_short v[16:17], v0 offset:3584
	v_add_co_u32_e32 v0, vcc, s63, v110
	v_cvt_pk_bf16_f32 v2, v4, s0
	s_nop 0
	v_addc_co_u32_e32 v1, vcc, 0, v111, vcc
	v_cvt_pk_bf16_f32 v4, v20, s0
	s_mov_b32 s0, 0x14000
	flat_store_short v[0:1], v2 offset:1536
	v_add_co_u32_e32 v2, vcc, s0, v110
	s_nop 1
	v_addc_co_u32_e32 v3, vcc, 0, v111, vcc
	flat_store_short v[2:3], v4 offset:1536
	v_cvt_pk_bf16_f32 v4, v5, s0
	flat_store_short v[0:1], v4 offset:3584
	v_cvt_pk_bf16_f32 v0, v21, s0
	flat_store_short v[2:3], v0 offset:3584
	v_add_co_u32_e32 v0, vcc, s91, v110
	v_cvt_pk_bf16_f32 v2, v6, s0
	s_nop 0
	v_addc_co_u32_e32 v1, vcc, 0, v111, vcc
	v_cvt_pk_bf16_f32 v4, v22, s0
	s_mov_b32 s0, 0x15000
	flat_store_short v[0:1], v2 offset:1536
	v_add_co_u32_e32 v2, vcc, s0, v110
	s_nop 1
	v_addc_co_u32_e32 v3, vcc, 0, v111, vcc
	flat_store_short v[2:3], v4 offset:1536
	v_cvt_pk_bf16_f32 v4, v7, s0
	flat_store_short v[0:1], v4 offset:3584
	v_cvt_pk_bf16_f32 v0, v23, s0
	flat_store_short v[2:3], v0 offset:3584
	v_add_co_u32_e32 v0, vcc, s68, v110
	v_cvt_pk_bf16_f32 v2, v8, s0
	s_nop 0
	v_addc_co_u32_e32 v1, vcc, 0, v111, vcc
	v_cvt_pk_bf16_f32 v4, v24, s0
	s_mov_b32 s0, 0x18000
	flat_store_short v[0:1], v2 offset:1536
	v_add_co_u32_e32 v2, vcc, s0, v110
	s_nop 1
	v_addc_co_u32_e32 v3, vcc, 0, v111, vcc
	flat_store_short v[2:3], v4 offset:1536
	v_cvt_pk_bf16_f32 v4, v9, s0
	flat_store_short v[0:1], v4 offset:3584
	v_cvt_pk_bf16_f32 v0, v25, s0
	flat_store_short v[2:3], v0 offset:3584
	v_add_co_u32_e32 v0, vcc, s92, v110
	v_cvt_pk_bf16_f32 v2, v10, s0
	s_nop 0
	v_addc_co_u32_e32 v1, vcc, 0, v111, vcc
	v_cvt_pk_bf16_f32 v4, v26, s0
	s_mov_b32 s0, 0x19000
	flat_store_short v[0:1], v2 offset:1536
	v_add_co_u32_e32 v2, vcc, s0, v110
	s_nop 1
	v_addc_co_u32_e32 v3, vcc, 0, v111, vcc
	flat_store_short v[2:3], v4 offset:1536
	v_cvt_pk_bf16_f32 v4, v11, s0
	flat_store_short v[0:1], v4 offset:3584
	v_cvt_pk_bf16_f32 v0, v27, s0
	flat_store_short v[2:3], v0 offset:3584
	v_add_co_u32_e32 v0, vcc, s88, v110
	v_cvt_pk_bf16_f32 v2, v12, s0
	s_nop 0
	v_addc_co_u32_e32 v1, vcc, 0, v111, vcc
	v_cvt_pk_bf16_f32 v4, v28, s0
	s_mov_b32 s0, 0x1c000
	flat_store_short v[0:1], v2 offset:1536
	v_add_co_u32_e32 v2, vcc, s0, v110
	s_nop 1
	v_addc_co_u32_e32 v3, vcc, 0, v111, vcc
	flat_store_short v[2:3], v4 offset:1536
	v_cvt_pk_bf16_f32 v4, v13, s0
	flat_store_short v[0:1], v4 offset:3584
	v_cvt_pk_bf16_f32 v0, v29, s0
	flat_store_short v[2:3], v0 offset:3584
	v_cvt_pk_bf16_f32 v2, v14, s0
	s_mov_b32 s0, 0xd000
	v_add_co_u32_e32 v0, vcc, s0, v110
	v_cvt_pk_bf16_f32 v4, v30, s0
	s_nop 0
	v_addc_co_u32_e32 v1, vcc, 0, v111, vcc
	flat_store_short v[0:1], v2 offset:1536
	v_add_co_u32_e32 v2, vcc, 0x1d000, v110
	s_nop 1
	v_addc_co_u32_e32 v3, vcc, 0, v111, vcc
	flat_store_short v[2:3], v4 offset:1536
	v_cvt_pk_bf16_f32 v4, v15, s0
	flat_store_short v[0:1], v4 offset:3584
	v_cvt_pk_bf16_f32 v0, v31, s0
	flat_store_short v[2:3], v0 offset:3584
	s_cbranch_scc1 .LBB0_242
